# mixer schedule: part order within bins rearranged (half of CLP bins P-first, odd CLPP bins L-last) to spread bandwidth-bound L parts; plus embed rewrite, permlane-swap reductions
# speedup vs baseline: 1.0336x; 1.0148x over previous
.LBB0_191:
	v_lshlrev_b32_e32 v120, 4, v30
	s_lshl_b32 s18, s44, 12
	s_add_u32 s18, s12, s18
	s_addc_u32 s19, s13, 0
	global_load_dwordx4 v[64:67], v120, s[18:19] nt
	global_load_dwordx4 v[68:71], v120, s[18:19] offset:1024 nt
	global_load_dwordx4 v[72:75], v120, s[18:19] offset:2048 nt
	global_load_dwordx4 v[76:79], v120, s[18:19] offset:3072 nt
	s_and_saveexec_b64 s[8:9], s[6:7]
	s_cbranch_execz .LBB0_204
	v_mov_b32_e32 v1, 0
	global_load_dword v2, v1, s[4:5] sc1
	s_movk_i32 s3, 0xff
	s_waitcnt vmcnt(0)
	v_cmp_lt_u32_e32 vcc, s3, v2
	s_cbranch_vccnz .LBB0_203
	s_mov_b32 s10, 0xffff8
	s_movk_i32 s11, 0x100
	s_branch .LBB0_195

.LBB0_204:
	s_or_b64 exec, exec, s[8:9]
	s_cmpk_gt_i32 s44, 0x47ff
	s_barrier
	s_cbranch_scc1 .LBB0_221
	v_lshlrev_b32_e32 v120, 4, v30
	v_lshlrev_b32_e32 v121, 3, v30
	v_mov_b32_e32 v116, 0x358637bd
	v_mov_b32_e32 v117, 0x260
	s_mov_b32 s3, 0xf800000
	s_lshl_b32 s14, s44, 12
	s_add_u32 s4, s12, s14
	s_addc_u32 s5, s13, 0
	s_add_u32 s22, s16, s14
	s_addc_u32 s23, s17, 0
	s_mov_b64 s[6:7], s[38:39]
	s_add_u32 s8, s38, 0x1000
	s_addc_u32 s9, s39, 0
	s_lshl_b32 s15, s44, 11
	s_add_u32 s10, s48, s15
	s_addc_u32 s11, s49, 0
	s_add_u32 s10, s10, 0x9300000
	s_addc_u32 s11, s11, 0
	s_add_u32 s12, s48, s15
	s_addc_u32 s13, s49, 0
	s_add_u32 s12, s12, 0x1e00000
	s_addc_u32 s13, s13, 0
	s_lshr_b32 s14, s44, 6
	s_lshl_b32 s14, s14, 11
	s_add_u32 s18, s48, s14
	s_addc_u32 s19, s49, 0
	s_add_u32 s18, s18, 0x190000
	s_addc_u32 s19, s19, 0
	s_and_b32 s14, s44, 63
	s_lshl_b32 s14, s14, 11
	s_add_u32 s20, s48, s14
	s_addc_u32 s21, s49, 0
	s_add_u32 s20, s20, 0x190000
	s_addc_u32 s21, s21, 0
	global_load_dwordx4 v[100:103], v120, s[24:25]
	global_load_dwordx4 v[104:107], v120, s[24:25] offset:1024
	global_load_dwordx4 v[108:111], v120, s[24:25] offset:2048
	global_load_dwordx4 v[112:115], v120, s[24:25] offset:3072
	global_load_dwordx4 v[84:87], v120, s[18:19]
	global_load_dwordx4 v[88:91], v120, s[18:19] offset:1024
	global_load_dwordx4 v[92:95], v120, s[20:21]
	global_load_dwordx4 v[96:99], v120, s[20:21] offset:1024
	global_load_dwordx4 v[16:19], v120, s[8:9]
	global_load_dwordx4 v[20:23], v120, s[8:9] offset:1024
	global_load_dwordx4 v[24:27], v120, s[8:9] offset:2048
	global_load_dwordx4 v[28:31], v120, s[8:9] offset:3072
	global_load_dwordx4 v[32:35], v120, s[6:7]
	global_load_dwordx4 v[36:39], v120, s[6:7] offset:1024
	global_load_dwordx4 v[40:43], v120, s[6:7] offset:2048
	global_load_dwordx4 v[44:47], v120, s[6:7] offset:3072
	s_add_u32 s4, s4, 0x800000
	s_addc_u32 s5, s5, 0
	s_add_u32 s6, s6, 0x3000
	s_addc_u32 s7, s7, 0
	s_add_u32 s8, s8, 0x3000
	s_addc_u32 s9, s9, 0
	global_load_dwordx4 v[128:131], v120, s[4:5] nt
	global_load_dwordx4 v[132:135], v120, s[4:5] offset:1024 nt
	global_load_dwordx4 v[136:139], v120, s[4:5] offset:2048 nt
	global_load_dwordx4 v[140:143], v120, s[4:5] offset:3072 nt
	global_load_dwordx4 v[144:147], v120, s[8:9]
	global_load_dwordx4 v[148:151], v120, s[8:9] offset:1024
	global_load_dwordx4 v[152:155], v120, s[8:9] offset:2048
	global_load_dwordx4 v[156:159], v120, s[8:9] offset:3072
	global_load_dwordx4 v[160:163], v120, s[6:7]
	global_load_dwordx4 v[164:167], v120, s[6:7] offset:1024
	global_load_dwordx4 v[168:171], v120, s[6:7] offset:2048
	global_load_dwordx4 v[172:175], v120, s[6:7] offset:3072
	s_waitcnt vmcnt(12)
	v_pk_add_f32 v[64:65], v[64:65], v[84:85]
	v_pk_add_f32 v[66:67], v[66:67], v[86:87]
	v_pk_add_f32 v[68:69], v[68:69], v[88:89]
	v_pk_add_f32 v[70:71], v[70:71], v[90:91]
	v_pk_add_f32 v[72:73], v[72:73], v[92:93]
	v_pk_add_f32 v[74:75], v[74:75], v[94:95]
	v_pk_add_f32 v[76:77], v[76:77], v[96:97]
	v_pk_add_f32 v[78:79], v[78:79], v[98:99]
	v_cvt_pk_bf16_f32 v176, v64, v65
	v_cvt_pk_bf16_f32 v177, v66, v67
	global_store_dwordx2 v121, v[176:177], s[10:11]
	v_cvt_pk_bf16_f32 v178, v68, v69
	v_cvt_pk_bf16_f32 v179, v70, v71
	global_store_dwordx2 v121, v[178:179], s[10:11] offset:512
	v_cvt_pk_bf16_f32 v180, v72, v73
	v_cvt_pk_bf16_f32 v181, v74, v75
	global_store_dwordx2 v121, v[180:181], s[10:11] offset:1024
	v_cvt_pk_bf16_f32 v182, v76, v77
	v_cvt_pk_bf16_f32 v183, v78, v79
	global_store_dwordx2 v121, v[182:183], s[10:11] offset:1536
	v_mul_f32_e32 v192, v65, v65
	v_mul_f32_e32 v193, v67, v67
	v_mul_f32_e32 v194, v69, v69
	v_mul_f32_e32 v195, v71, v71
	v_mul_f32_e32 v196, v73, v73
	v_mul_f32_e32 v197, v75, v75
	v_pk_mul_f32 v[198:199], v[78:79], v[78:79]
	v_pk_mul_f32 v[200:201], v[76:77], v[76:77]
	v_fmac_f32_e32 v192, v64, v64
	v_fmac_f32_e32 v193, v66, v66
	v_fmac_f32_e32 v194, v68, v68
	v_fmac_f32_e32 v195, v70, v70
	v_fmac_f32_e32 v196, v72, v72
	v_fmac_f32_e32 v197, v74, v74
	v_add_f32_e32 v202, v201, v200
	v_add_f32_e32 v203, v198, v199
	v_add_f32_e32 v192, v192, v193
	v_add_f32_e32 v193, v194, v195
	v_add_f32_e32 v194, v196, v197
	v_add_f32_e32 v192, v192, v193
	v_add_f32_e32 v202, v202, v203
	v_add_f32_e32 v193, v192, v194
	v_add_f32_e32 v202, v193, v202
	s_nop 1
	v_add_f32_dpp v202, v202, v202 quad_perm:[1,0,3,2] row_mask:0xf bank_mask:0xf bound_ctrl:1
	s_nop 1
	v_add_f32_dpp v202, v202, v202 quad_perm:[2,3,0,1] row_mask:0xf bank_mask:0xf bound_ctrl:1
	s_nop 1
	v_add_f32_dpp v202, v202, v202 row_half_mirror row_mask:0xf bank_mask:0xf bound_ctrl:1
	s_nop 1
	v_add_f32_dpp v202, v202, v202 row_mirror row_mask:0xf bank_mask:0xf bound_ctrl:1
	s_nop 1
	v_readlane_b32 s14, v202, 16
	v_readlane_b32 s15, v202, 48
	v_readlane_b32 s18, v202, 0
	v_readlane_b32 s19, v202, 32
	s_nop 1
	v_mov_b32_e32 v202, s14
	v_mov_b32_e32 v203, s15
	v_pk_add_f32 v[202:203], s[18:19], v[202:203]
	s_nop 0
	v_add_f32_e32 v202, v202, v203
	v_fmamk_f32 v202, v202, 0x3a800000, v116
	v_mul_f32_e32 v203, 0x4f800000, v202
	v_cmp_gt_f32_e32 vcc, s3, v202
	s_nop 1
	v_cndmask_b32_e32 v202, v202, v203, vcc
	v_sqrt_f32_e32 v203, v202
	s_nop 0
	v_add_u32_e32 v204, -1, v203
	v_add_u32_e32 v205, 1, v203
	v_fma_f32 v206, -v204, v203, v202
	v_fma_f32 v207, -v205, v203, v202
	v_cmp_ge_f32_e64 s[20:21], 0, v206
	s_nop 1
	v_cndmask_b32_e64 v203, v203, v204, s[20:21]
	v_cmp_lt_f32_e64 s[20:21], 0, v207
	s_nop 1
	v_cndmask_b32_e64 v203, v203, v205, s[20:21]
	v_mul_f32_e32 v204, 0x37800000, v203
	v_cndmask_b32_e32 v203, v203, v204, vcc
	v_cmp_class_f32_e32 vcc, v202, v117
	s_nop 1
	v_cndmask_b32_e32 v204, v203, v202, vcc
	v_div_scale_f32 v205, s[20:21], v204, v204, 1.0
	v_rcp_f32_e32 v206, v205
	v_div_scale_f32 v207, vcc, 1.0, v204, 1.0
	s_nop 0
	v_fma_f32 v208, -v205, v206, 1.0
	v_fmac_f32_e32 v206, v208, v206
	v_mul_f32_e32 v208, v207, v206
	v_fma_f32 v209, -v205, v208, v207
	v_fmac_f32_e32 v208, v209, v206
	v_fma_f32 v205, -v205, v208, v207
	v_div_fmas_f32 v205, v205, v206, v208
	v_div_fixup_f32 v210, v205, v204, 1.0
	v_pk_add_f32 v[16:17], v[16:17], 1.0 op_sel_hi:[1,0]
	v_pk_add_f32 v[18:19], v[18:19], 1.0 op_sel_hi:[1,0]
	v_pk_mul_f32 v[16:17], v[100:101], v[16:17]
	v_pk_mul_f32 v[18:19], v[102:103], v[18:19]
	v_pk_mul_f32 v[64:65], v[64:65], v[210:211] op_sel_hi:[1,0]
	v_pk_mul_f32 v[66:67], v[66:67], v[210:211] op_sel_hi:[1,0]
	v_pk_fma_f32 v[64:65], v[16:17], v[64:65], v[32:33]
	v_pk_fma_f32 v[66:67], v[18:19], v[66:67], v[34:35]
	v_cvt_pk_bf16_f32 v184, v64, v65
	v_cvt_pk_bf16_f32 v185, v66, v67
	global_store_dwordx2 v121, v[184:185], s[12:13]
	v_pk_add_f32 v[20:21], v[20:21], 1.0 op_sel_hi:[1,0]
	v_pk_add_f32 v[22:23], v[22:23], 1.0 op_sel_hi:[1,0]
	v_pk_mul_f32 v[20:21], v[104:105], v[20:21]
	v_pk_mul_f32 v[22:23], v[106:107], v[22:23]
	v_pk_mul_f32 v[68:69], v[68:69], v[210:211] op_sel_hi:[1,0]
	v_pk_mul_f32 v[70:71], v[70:71], v[210:211] op_sel_hi:[1,0]
	v_pk_fma_f32 v[68:69], v[20:21], v[68:69], v[36:37]
	v_pk_fma_f32 v[70:71], v[22:23], v[70:71], v[38:39]
	v_cvt_pk_bf16_f32 v186, v68, v69
	v_cvt_pk_bf16_f32 v187, v70, v71
	global_store_dwordx2 v121, v[186:187], s[12:13] offset:512
	v_pk_add_f32 v[24:25], v[24:25], 1.0 op_sel_hi:[1,0]
	v_pk_add_f32 v[26:27], v[26:27], 1.0 op_sel_hi:[1,0]
	v_pk_mul_f32 v[24:25], v[108:109], v[24:25]
	v_pk_mul_f32 v[26:27], v[110:111], v[26:27]
	v_pk_mul_f32 v[72:73], v[72:73], v[210:211] op_sel_hi:[1,0]
	v_pk_mul_f32 v[74:75], v[74:75], v[210:211] op_sel_hi:[1,0]
	v_pk_fma_f32 v[72:73], v[24:25], v[72:73], v[40:41]
	v_pk_fma_f32 v[74:75], v[26:27], v[74:75], v[42:43]
	v_cvt_pk_bf16_f32 v188, v72, v73
	v_cvt_pk_bf16_f32 v189, v74, v75
	global_store_dwordx2 v121, v[188:189], s[12:13] offset:1024
	v_pk_add_f32 v[28:29], v[28:29], 1.0 op_sel_hi:[1,0]
	v_pk_add_f32 v[30:31], v[30:31], 1.0 op_sel_hi:[1,0]
	v_pk_mul_f32 v[28:29], v[112:113], v[28:29]
	v_pk_mul_f32 v[30:31], v[114:115], v[30:31]
	v_pk_mul_f32 v[76:77], v[76:77], v[210:211] op_sel_hi:[1,0]
	v_pk_mul_f32 v[78:79], v[78:79], v[210:211] op_sel_hi:[1,0]
	v_pk_fma_f32 v[76:77], v[28:29], v[76:77], v[44:45]
	v_pk_fma_f32 v[78:79], v[30:31], v[78:79], v[46:47]
	v_cvt_pk_bf16_f32 v190, v76, v77
	v_cvt_pk_bf16_f32 v191, v78, v79
	global_store_dwordx2 v121, v[190:191], s[12:13] offset:1536
	s_add_u32 s10, s10, 0x400000
	s_addc_u32 s11, s11, 0
	s_add_u32 s12, s12, 0x400000
	s_addc_u32 s13, s13, 0
	s_add_u32 s4, s4, 0x800000
	s_addc_u32 s5, s5, 0
	s_add_u32 s6, s6, 0x3000
	s_addc_u32 s7, s7, 0
	s_add_u32 s8, s8, 0x3000
	s_addc_u32 s9, s9, 0
	global_load_dwordx4 v[64:67], v120, s[4:5] nt
	global_load_dwordx4 v[68:71], v120, s[4:5] offset:1024 nt
	global_load_dwordx4 v[72:75], v120, s[4:5] offset:2048 nt
	global_load_dwordx4 v[76:79], v120, s[4:5] offset:3072 nt
	global_load_dwordx4 v[16:19], v120, s[8:9]
	global_load_dwordx4 v[20:23], v120, s[8:9] offset:1024
	global_load_dwordx4 v[24:27], v120, s[8:9] offset:2048
	global_load_dwordx4 v[28:31], v120, s[8:9] offset:3072
	global_load_dwordx4 v[32:35], v120, s[6:7]
	global_load_dwordx4 v[36:39], v120, s[6:7] offset:1024
	global_load_dwordx4 v[40:43], v120, s[6:7] offset:2048
	global_load_dwordx4 v[44:47], v120, s[6:7] offset:3072
	s_waitcnt vmcnt(20)
	v_pk_add_f32 v[128:129], v[128:129], v[84:85]
	v_pk_add_f32 v[130:131], v[130:131], v[86:87]
	v_pk_add_f32 v[132:133], v[132:133], v[88:89]
	v_pk_add_f32 v[134:135], v[134:135], v[90:91]
	v_pk_add_f32 v[136:137], v[136:137], v[92:93]
	v_pk_add_f32 v[138:139], v[138:139], v[94:95]
	v_pk_add_f32 v[140:141], v[140:141], v[96:97]
	v_pk_add_f32 v[142:143], v[142:143], v[98:99]
	v_cvt_pk_bf16_f32 v176, v128, v129
	v_cvt_pk_bf16_f32 v177, v130, v131
	global_store_dwordx2 v121, v[176:177], s[10:11]
	v_cvt_pk_bf16_f32 v178, v132, v133
	v_cvt_pk_bf16_f32 v179, v134, v135
	global_store_dwordx2 v121, v[178:179], s[10:11] offset:512
	v_cvt_pk_bf16_f32 v180, v136, v137
	v_cvt_pk_bf16_f32 v181, v138, v139
	global_store_dwordx2 v121, v[180:181], s[10:11] offset:1024
	v_cvt_pk_bf16_f32 v182, v140, v141
	v_cvt_pk_bf16_f32 v183, v142, v143
	global_store_dwordx2 v121, v[182:183], s[10:11] offset:1536
	v_mul_f32_e32 v192, v129, v129
	v_mul_f32_e32 v193, v131, v131
	v_mul_f32_e32 v194, v133, v133
	v_mul_f32_e32 v195, v135, v135
	v_mul_f32_e32 v196, v137, v137
	v_mul_f32_e32 v197, v139, v139
	v_pk_mul_f32 v[198:199], v[142:143], v[142:143]
	v_pk_mul_f32 v[200:201], v[140:141], v[140:141]
	v_fmac_f32_e32 v192, v128, v128
	v_fmac_f32_e32 v193, v130, v130
	v_fmac_f32_e32 v194, v132, v132
	v_fmac_f32_e32 v195, v134, v134
	v_fmac_f32_e32 v196, v136, v136
	v_fmac_f32_e32 v197, v138, v138
	v_add_f32_e32 v202, v201, v200
	v_add_f32_e32 v203, v198, v199
	v_add_f32_e32 v192, v192, v193
	v_add_f32_e32 v193, v194, v195
	v_add_f32_e32 v194, v196, v197
	v_add_f32_e32 v192, v192, v193
	v_add_f32_e32 v202, v202, v203
	v_add_f32_e32 v193, v192, v194
	v_add_f32_e32 v202, v193, v202
	s_nop 1
	v_add_f32_dpp v202, v202, v202 quad_perm:[1,0,3,2] row_mask:0xf bank_mask:0xf bound_ctrl:1
	s_nop 1
	v_add_f32_dpp v202, v202, v202 quad_perm:[2,3,0,1] row_mask:0xf bank_mask:0xf bound_ctrl:1
	s_nop 1
	v_add_f32_dpp v202, v202, v202 row_half_mirror row_mask:0xf bank_mask:0xf bound_ctrl:1
	s_nop 1
	v_add_f32_dpp v202, v202, v202 row_mirror row_mask:0xf bank_mask:0xf bound_ctrl:1
	s_nop 1
	v_readlane_b32 s14, v202, 16
	v_readlane_b32 s15, v202, 48
	v_readlane_b32 s18, v202, 0
	v_readlane_b32 s19, v202, 32
	s_nop 1
	v_mov_b32_e32 v202, s14
	v_mov_b32_e32 v203, s15
	v_pk_add_f32 v[202:203], s[18:19], v[202:203]
	s_nop 0
	v_add_f32_e32 v202, v202, v203
	v_fmamk_f32 v202, v202, 0x3a800000, v116
	v_mul_f32_e32 v203, 0x4f800000, v202
	v_cmp_gt_f32_e32 vcc, s3, v202
	s_nop 1
	v_cndmask_b32_e32 v202, v202, v203, vcc
	v_sqrt_f32_e32 v203, v202
	s_nop 0
	v_add_u32_e32 v204, -1, v203
	v_add_u32_e32 v205, 1, v203
	v_fma_f32 v206, -v204, v203, v202
	v_fma_f32 v207, -v205, v203, v202
	v_cmp_ge_f32_e64 s[20:21], 0, v206
	s_nop 1
	v_cndmask_b32_e64 v203, v203, v204, s[20:21]
	v_cmp_lt_f32_e64 s[20:21], 0, v207
	s_nop 1
	v_cndmask_b32_e64 v203, v203, v205, s[20:21]
	v_mul_f32_e32 v204, 0x37800000, v203
	v_cndmask_b32_e32 v203, v203, v204, vcc
	v_cmp_class_f32_e32 vcc, v202, v117
	s_nop 1
	v_cndmask_b32_e32 v204, v203, v202, vcc
	v_div_scale_f32 v205, s[20:21], v204, v204, 1.0
	v_rcp_f32_e32 v206, v205
	v_div_scale_f32 v207, vcc, 1.0, v204, 1.0
	s_nop 0
	v_fma_f32 v208, -v205, v206, 1.0
	v_fmac_f32_e32 v206, v208, v206
	v_mul_f32_e32 v208, v207, v206
	v_fma_f32 v209, -v205, v208, v207
	v_fmac_f32_e32 v208, v209, v206
	v_fma_f32 v205, -v205, v208, v207
	v_div_fmas_f32 v205, v205, v206, v208
	v_div_fixup_f32 v210, v205, v204, 1.0
	v_pk_add_f32 v[144:145], v[144:145], 1.0 op_sel_hi:[1,0]
	v_pk_add_f32 v[146:147], v[146:147], 1.0 op_sel_hi:[1,0]
	v_pk_mul_f32 v[144:145], v[100:101], v[144:145]
	v_pk_mul_f32 v[146:147], v[102:103], v[146:147]
	v_pk_mul_f32 v[128:129], v[128:129], v[210:211] op_sel_hi:[1,0]
	v_pk_mul_f32 v[130:131], v[130:131], v[210:211] op_sel_hi:[1,0]
	v_pk_fma_f32 v[128:129], v[144:145], v[128:129], v[160:161]
	v_pk_fma_f32 v[130:131], v[146:147], v[130:131], v[162:163]
	v_cvt_pk_bf16_f32 v184, v128, v129
	v_cvt_pk_bf16_f32 v185, v130, v131
	global_store_dwordx2 v121, v[184:185], s[12:13]
	v_pk_add_f32 v[148:149], v[148:149], 1.0 op_sel_hi:[1,0]
	v_pk_add_f32 v[150:151], v[150:151], 1.0 op_sel_hi:[1,0]
	v_pk_mul_f32 v[148:149], v[104:105], v[148:149]
	v_pk_mul_f32 v[150:151], v[106:107], v[150:151]
	v_pk_mul_f32 v[132:133], v[132:133], v[210:211] op_sel_hi:[1,0]
	v_pk_mul_f32 v[134:135], v[134:135], v[210:211] op_sel_hi:[1,0]
	v_pk_fma_f32 v[132:133], v[148:149], v[132:133], v[164:165]
	v_pk_fma_f32 v[134:135], v[150:151], v[134:135], v[166:167]
	v_cvt_pk_bf16_f32 v186, v132, v133
	v_cvt_pk_bf16_f32 v187, v134, v135
	global_store_dwordx2 v121, v[186:187], s[12:13] offset:512
	v_pk_add_f32 v[152:153], v[152:153], 1.0 op_sel_hi:[1,0]
	v_pk_add_f32 v[154:155], v[154:155], 1.0 op_sel_hi:[1,0]
	v_pk_mul_f32 v[152:153], v[108:109], v[152:153]
	v_pk_mul_f32 v[154:155], v[110:111], v[154:155]
	v_pk_mul_f32 v[136:137], v[136:137], v[210:211] op_sel_hi:[1,0]
	v_pk_mul_f32 v[138:139], v[138:139], v[210:211] op_sel_hi:[1,0]
	v_pk_fma_f32 v[136:137], v[152:153], v[136:137], v[168:169]
	v_pk_fma_f32 v[138:139], v[154:155], v[138:139], v[170:171]
	v_cvt_pk_bf16_f32 v188, v136, v137
	v_cvt_pk_bf16_f32 v189, v138, v139
	global_store_dwordx2 v121, v[188:189], s[12:13] offset:1024
	v_pk_add_f32 v[156:157], v[156:157], 1.0 op_sel_hi:[1,0]
	v_pk_add_f32 v[158:159], v[158:159], 1.0 op_sel_hi:[1,0]
	v_pk_mul_f32 v[156:157], v[112:113], v[156:157]
	v_pk_mul_f32 v[158:159], v[114:115], v[158:159]
	v_pk_mul_f32 v[140:141], v[140:141], v[210:211] op_sel_hi:[1,0]
	v_pk_mul_f32 v[142:143], v[142:143], v[210:211] op_sel_hi:[1,0]
	v_pk_fma_f32 v[140:141], v[156:157], v[140:141], v[172:173]
	v_pk_fma_f32 v[142:143], v[158:159], v[142:143], v[174:175]
	v_cvt_pk_bf16_f32 v190, v140, v141
	v_cvt_pk_bf16_f32 v191, v142, v143
	global_store_dwordx2 v121, v[190:191], s[12:13] offset:1536
	s_add_u32 s10, s10, 0x400000
	s_addc_u32 s11, s11, 0
	s_add_u32 s12, s12, 0x400000
	s_addc_u32 s13, s13, 0
	s_add_u32 s4, s4, 0x800000
	s_addc_u32 s5, s5, 0
	s_add_u32 s6, s6, 0x3000
	s_addc_u32 s7, s7, 0
	s_add_u32 s8, s8, 0x3000
	s_addc_u32 s9, s9, 0
	global_load_dwordx4 v[128:131], v120, s[4:5] nt
	global_load_dwordx4 v[132:135], v120, s[4:5] offset:1024 nt
	global_load_dwordx4 v[136:139], v120, s[4:5] offset:2048 nt
	global_load_dwordx4 v[140:143], v120, s[4:5] offset:3072 nt
	global_load_dwordx4 v[144:147], v120, s[8:9]
	global_load_dwordx4 v[148:151], v120, s[8:9] offset:1024
	global_load_dwordx4 v[152:155], v120, s[8:9] offset:2048
	global_load_dwordx4 v[156:159], v120, s[8:9] offset:3072
	global_load_dwordx4 v[160:163], v120, s[6:7]
	global_load_dwordx4 v[164:167], v120, s[6:7] offset:1024
	global_load_dwordx4 v[168:171], v120, s[6:7] offset:2048
	global_load_dwordx4 v[172:175], v120, s[6:7] offset:3072
	s_waitcnt vmcnt(20)
	v_pk_add_f32 v[64:65], v[64:65], v[84:85]
	v_pk_add_f32 v[66:67], v[66:67], v[86:87]
	v_pk_add_f32 v[68:69], v[68:69], v[88:89]
	v_pk_add_f32 v[70:71], v[70:71], v[90:91]
	v_pk_add_f32 v[72:73], v[72:73], v[92:93]
	v_pk_add_f32 v[74:75], v[74:75], v[94:95]
	v_pk_add_f32 v[76:77], v[76:77], v[96:97]
	v_pk_add_f32 v[78:79], v[78:79], v[98:99]
	v_cvt_pk_bf16_f32 v176, v64, v65
	v_cvt_pk_bf16_f32 v177, v66, v67
	global_store_dwordx2 v121, v[176:177], s[10:11]
	v_cvt_pk_bf16_f32 v178, v68, v69
	v_cvt_pk_bf16_f32 v179, v70, v71
	global_store_dwordx2 v121, v[178:179], s[10:11] offset:512
	v_cvt_pk_bf16_f32 v180, v72, v73
	v_cvt_pk_bf16_f32 v181, v74, v75
	global_store_dwordx2 v121, v[180:181], s[10:11] offset:1024
	v_cvt_pk_bf16_f32 v182, v76, v77
	v_cvt_pk_bf16_f32 v183, v78, v79
	global_store_dwordx2 v121, v[182:183], s[10:11] offset:1536
	v_mul_f32_e32 v192, v65, v65
	v_mul_f32_e32 v193, v67, v67
	v_mul_f32_e32 v194, v69, v69
	v_mul_f32_e32 v195, v71, v71
	v_mul_f32_e32 v196, v73, v73
	v_mul_f32_e32 v197, v75, v75
	v_pk_mul_f32 v[198:199], v[78:79], v[78:79]
	v_pk_mul_f32 v[200:201], v[76:77], v[76:77]
	v_fmac_f32_e32 v192, v64, v64
	v_fmac_f32_e32 v193, v66, v66
	v_fmac_f32_e32 v194, v68, v68
	v_fmac_f32_e32 v195, v70, v70
	v_fmac_f32_e32 v196, v72, v72
	v_fmac_f32_e32 v197, v74, v74
	v_add_f32_e32 v202, v201, v200
	v_add_f32_e32 v203, v198, v199
	v_add_f32_e32 v192, v192, v193
	v_add_f32_e32 v193, v194, v195
	v_add_f32_e32 v194, v196, v197
	v_add_f32_e32 v192, v192, v193
	v_add_f32_e32 v202, v202, v203
	v_add_f32_e32 v193, v192, v194
	v_add_f32_e32 v202, v193, v202
	s_nop 1
	v_add_f32_dpp v202, v202, v202 quad_perm:[1,0,3,2] row_mask:0xf bank_mask:0xf bound_ctrl:1
	s_nop 1
	v_add_f32_dpp v202, v202, v202 quad_perm:[2,3,0,1] row_mask:0xf bank_mask:0xf bound_ctrl:1
	s_nop 1
	v_add_f32_dpp v202, v202, v202 row_half_mirror row_mask:0xf bank_mask:0xf bound_ctrl:1
	s_nop 1
	v_add_f32_dpp v202, v202, v202 row_mirror row_mask:0xf bank_mask:0xf bound_ctrl:1
	s_nop 1
	v_readlane_b32 s14, v202, 16
	v_readlane_b32 s15, v202, 48
	v_readlane_b32 s18, v202, 0
	v_readlane_b32 s19, v202, 32
	s_nop 1
	v_mov_b32_e32 v202, s14
	v_mov_b32_e32 v203, s15
	v_pk_add_f32 v[202:203], s[18:19], v[202:203]
	s_nop 0
	v_add_f32_e32 v202, v202, v203
	v_fmamk_f32 v202, v202, 0x3a800000, v116
	v_mul_f32_e32 v203, 0x4f800000, v202
	v_cmp_gt_f32_e32 vcc, s3, v202
	s_nop 1
	v_cndmask_b32_e32 v202, v202, v203, vcc
	v_sqrt_f32_e32 v203, v202
	s_nop 0
	v_add_u32_e32 v204, -1, v203
	v_add_u32_e32 v205, 1, v203
	v_fma_f32 v206, -v204, v203, v202
	v_fma_f32 v207, -v205, v203, v202
	v_cmp_ge_f32_e64 s[20:21], 0, v206
	s_nop 1
	v_cndmask_b32_e64 v203, v203, v204, s[20:21]
	v_cmp_lt_f32_e64 s[20:21], 0, v207
	s_nop 1
	v_cndmask_b32_e64 v203, v203, v205, s[20:21]
	v_mul_f32_e32 v204, 0x37800000, v203
	v_cndmask_b32_e32 v203, v203, v204, vcc
	v_cmp_class_f32_e32 vcc, v202, v117
	s_nop 1
	v_cndmask_b32_e32 v204, v203, v202, vcc
	v_div_scale_f32 v205, s[20:21], v204, v204, 1.0
	v_rcp_f32_e32 v206, v205
	v_div_scale_f32 v207, vcc, 1.0, v204, 1.0
	s_nop 0
	v_fma_f32 v208, -v205, v206, 1.0
	v_fmac_f32_e32 v206, v208, v206
	v_mul_f32_e32 v208, v207, v206
	v_fma_f32 v209, -v205, v208, v207
	v_fmac_f32_e32 v208, v209, v206
	v_fma_f32 v205, -v205, v208, v207
	v_div_fmas_f32 v205, v205, v206, v208
	v_div_fixup_f32 v210, v205, v204, 1.0
	v_pk_add_f32 v[16:17], v[16:17], 1.0 op_sel_hi:[1,0]
	v_pk_add_f32 v[18:19], v[18:19], 1.0 op_sel_hi:[1,0]
	v_pk_mul_f32 v[16:17], v[100:101], v[16:17]
	v_pk_mul_f32 v[18:19], v[102:103], v[18:19]
	v_pk_mul_f32 v[64:65], v[64:65], v[210:211] op_sel_hi:[1,0]
	v_pk_mul_f32 v[66:67], v[66:67], v[210:211] op_sel_hi:[1,0]
	v_pk_fma_f32 v[64:65], v[16:17], v[64:65], v[32:33]
	v_pk_fma_f32 v[66:67], v[18:19], v[66:67], v[34:35]
	v_cvt_pk_bf16_f32 v184, v64, v65
	v_cvt_pk_bf16_f32 v185, v66, v67
	global_store_dwordx2 v121, v[184:185], s[12:13]
	v_pk_add_f32 v[20:21], v[20:21], 1.0 op_sel_hi:[1,0]
	v_pk_add_f32 v[22:23], v[22:23], 1.0 op_sel_hi:[1,0]
	v_pk_mul_f32 v[20:21], v[104:105], v[20:21]
	v_pk_mul_f32 v[22:23], v[106:107], v[22:23]
	v_pk_mul_f32 v[68:69], v[68:69], v[210:211] op_sel_hi:[1,0]
	v_pk_mul_f32 v[70:71], v[70:71], v[210:211] op_sel_hi:[1,0]
	v_pk_fma_f32 v[68:69], v[20:21], v[68:69], v[36:37]
	v_pk_fma_f32 v[70:71], v[22:23], v[70:71], v[38:39]
	v_cvt_pk_bf16_f32 v186, v68, v69
	v_cvt_pk_bf16_f32 v187, v70, v71
	global_store_dwordx2 v121, v[186:187], s[12:13] offset:512
	v_pk_add_f32 v[24:25], v[24:25], 1.0 op_sel_hi:[1,0]
	v_pk_add_f32 v[26:27], v[26:27], 1.0 op_sel_hi:[1,0]
	v_pk_mul_f32 v[24:25], v[108:109], v[24:25]
	v_pk_mul_f32 v[26:27], v[110:111], v[26:27]
	v_pk_mul_f32 v[72:73], v[72:73], v[210:211] op_sel_hi:[1,0]
	v_pk_mul_f32 v[74:75], v[74:75], v[210:211] op_sel_hi:[1,0]
	v_pk_fma_f32 v[72:73], v[24:25], v[72:73], v[40:41]
	v_pk_fma_f32 v[74:75], v[26:27], v[74:75], v[42:43]
	v_cvt_pk_bf16_f32 v188, v72, v73
	v_cvt_pk_bf16_f32 v189, v74, v75
	global_store_dwordx2 v121, v[188:189], s[12:13] offset:1024
	v_pk_add_f32 v[28:29], v[28:29], 1.0 op_sel_hi:[1,0]
	v_pk_add_f32 v[30:31], v[30:31], 1.0 op_sel_hi:[1,0]
	v_pk_mul_f32 v[28:29], v[112:113], v[28:29]
	v_pk_mul_f32 v[30:31], v[114:115], v[30:31]
	v_pk_mul_f32 v[76:77], v[76:77], v[210:211] op_sel_hi:[1,0]
	v_pk_mul_f32 v[78:79], v[78:79], v[210:211] op_sel_hi:[1,0]
	v_pk_fma_f32 v[76:77], v[28:29], v[76:77], v[44:45]
	v_pk_fma_f32 v[78:79], v[30:31], v[78:79], v[46:47]
	v_cvt_pk_bf16_f32 v190, v76, v77
	v_cvt_pk_bf16_f32 v191, v78, v79
	global_store_dwordx2 v121, v[190:191], s[12:13] offset:1536
	s_add_u32 s10, s10, 0x400000
	s_addc_u32 s11, s11, 0
	s_add_u32 s12, s12, 0x400000
	s_addc_u32 s13, s13, 0
	s_add_u32 s4, s4, 0x800000
	s_addc_u32 s5, s5, 0
	s_add_u32 s6, s6, 0x3000
	s_addc_u32 s7, s7, 0
	s_add_u32 s8, s8, 0x3000
	s_addc_u32 s9, s9, 0
	global_load_dwordx4 v[64:67], v120, s[4:5] nt
	global_load_dwordx4 v[68:71], v120, s[4:5] offset:1024 nt
	global_load_dwordx4 v[72:75], v120, s[4:5] offset:2048 nt
	global_load_dwordx4 v[76:79], v120, s[4:5] offset:3072 nt
	global_load_dwordx4 v[16:19], v120, s[8:9]
	global_load_dwordx4 v[20:23], v120, s[8:9] offset:1024
	global_load_dwordx4 v[24:27], v120, s[8:9] offset:2048
	global_load_dwordx4 v[28:31], v120, s[8:9] offset:3072
	global_load_dwordx4 v[32:35], v120, s[6:7]
	global_load_dwordx4 v[36:39], v120, s[6:7] offset:1024
	global_load_dwordx4 v[40:43], v120, s[6:7] offset:2048
	global_load_dwordx4 v[44:47], v120, s[6:7] offset:3072
	s_waitcnt vmcnt(20)
	v_pk_add_f32 v[128:129], v[128:129], v[84:85]
	v_pk_add_f32 v[130:131], v[130:131], v[86:87]
	v_pk_add_f32 v[132:133], v[132:133], v[88:89]
	v_pk_add_f32 v[134:135], v[134:135], v[90:91]
	v_pk_add_f32 v[136:137], v[136:137], v[92:93]
	v_pk_add_f32 v[138:139], v[138:139], v[94:95]
	v_pk_add_f32 v[140:141], v[140:141], v[96:97]
	v_pk_add_f32 v[142:143], v[142:143], v[98:99]
	v_cvt_pk_bf16_f32 v176, v128, v129
	v_cvt_pk_bf16_f32 v177, v130, v131
	global_store_dwordx2 v121, v[176:177], s[10:11]
	v_cvt_pk_bf16_f32 v178, v132, v133
	v_cvt_pk_bf16_f32 v179, v134, v135
	global_store_dwordx2 v121, v[178:179], s[10:11] offset:512
	v_cvt_pk_bf16_f32 v180, v136, v137
	v_cvt_pk_bf16_f32 v181, v138, v139
	global_store_dwordx2 v121, v[180:181], s[10:11] offset:1024
	v_cvt_pk_bf16_f32 v182, v140, v141
	v_cvt_pk_bf16_f32 v183, v142, v143
	global_store_dwordx2 v121, v[182:183], s[10:11] offset:1536
	v_mul_f32_e32 v192, v129, v129
	v_mul_f32_e32 v193, v131, v131
	v_mul_f32_e32 v194, v133, v133
	v_mul_f32_e32 v195, v135, v135
	v_mul_f32_e32 v196, v137, v137
	v_mul_f32_e32 v197, v139, v139
	v_pk_mul_f32 v[198:199], v[142:143], v[142:143]
	v_pk_mul_f32 v[200:201], v[140:141], v[140:141]
	v_fmac_f32_e32 v192, v128, v128
	v_fmac_f32_e32 v193, v130, v130
	v_fmac_f32_e32 v194, v132, v132
	v_fmac_f32_e32 v195, v134, v134
	v_fmac_f32_e32 v196, v136, v136
	v_fmac_f32_e32 v197, v138, v138
	v_add_f32_e32 v202, v201, v200
	v_add_f32_e32 v203, v198, v199
	v_add_f32_e32 v192, v192, v193
	v_add_f32_e32 v193, v194, v195
	v_add_f32_e32 v194, v196, v197
	v_add_f32_e32 v192, v192, v193
	v_add_f32_e32 v202, v202, v203
	v_add_f32_e32 v193, v192, v194
	v_add_f32_e32 v202, v193, v202
	s_nop 1
	v_add_f32_dpp v202, v202, v202 quad_perm:[1,0,3,2] row_mask:0xf bank_mask:0xf bound_ctrl:1
	s_nop 1
	v_add_f32_dpp v202, v202, v202 quad_perm:[2,3,0,1] row_mask:0xf bank_mask:0xf bound_ctrl:1
	s_nop 1
	v_add_f32_dpp v202, v202, v202 row_half_mirror row_mask:0xf bank_mask:0xf bound_ctrl:1
	s_nop 1
	v_add_f32_dpp v202, v202, v202 row_mirror row_mask:0xf bank_mask:0xf bound_ctrl:1
	s_nop 1
	v_readlane_b32 s14, v202, 16
	v_readlane_b32 s15, v202, 48
	v_readlane_b32 s18, v202, 0
	v_readlane_b32 s19, v202, 32
	s_nop 1
	v_mov_b32_e32 v202, s14
	v_mov_b32_e32 v203, s15
	v_pk_add_f32 v[202:203], s[18:19], v[202:203]
	s_nop 0
	v_add_f32_e32 v202, v202, v203
	v_fmamk_f32 v202, v202, 0x3a800000, v116
	v_mul_f32_e32 v203, 0x4f800000, v202
	v_cmp_gt_f32_e32 vcc, s3, v202
	s_nop 1
	v_cndmask_b32_e32 v202, v202, v203, vcc
	v_sqrt_f32_e32 v203, v202
	s_nop 0
	v_add_u32_e32 v204, -1, v203
	v_add_u32_e32 v205, 1, v203
	v_fma_f32 v206, -v204, v203, v202
	v_fma_f32 v207, -v205, v203, v202
	v_cmp_ge_f32_e64 s[20:21], 0, v206
	s_nop 1
	v_cndmask_b32_e64 v203, v203, v204, s[20:21]
	v_cmp_lt_f32_e64 s[20:21], 0, v207
	s_nop 1
	v_cndmask_b32_e64 v203, v203, v205, s[20:21]
	v_mul_f32_e32 v204, 0x37800000, v203
	v_cndmask_b32_e32 v203, v203, v204, vcc
	v_cmp_class_f32_e32 vcc, v202, v117
	s_nop 1
	v_cndmask_b32_e32 v204, v203, v202, vcc
	v_div_scale_f32 v205, s[20:21], v204, v204, 1.0
	v_rcp_f32_e32 v206, v205
	v_div_scale_f32 v207, vcc, 1.0, v204, 1.0
	s_nop 0
	v_fma_f32 v208, -v205, v206, 1.0
	v_fmac_f32_e32 v206, v208, v206
	v_mul_f32_e32 v208, v207, v206
	v_fma_f32 v209, -v205, v208, v207
	v_fmac_f32_e32 v208, v209, v206
	v_fma_f32 v205, -v205, v208, v207
	v_div_fmas_f32 v205, v205, v206, v208
	v_div_fixup_f32 v210, v205, v204, 1.0
	v_pk_add_f32 v[144:145], v[144:145], 1.0 op_sel_hi:[1,0]
	v_pk_add_f32 v[146:147], v[146:147], 1.0 op_sel_hi:[1,0]
	v_pk_mul_f32 v[144:145], v[100:101], v[144:145]
	v_pk_mul_f32 v[146:147], v[102:103], v[146:147]
	v_pk_mul_f32 v[128:129], v[128:129], v[210:211] op_sel_hi:[1,0]
	v_pk_mul_f32 v[130:131], v[130:131], v[210:211] op_sel_hi:[1,0]
	v_pk_fma_f32 v[128:129], v[144:145], v[128:129], v[160:161]
	v_pk_fma_f32 v[130:131], v[146:147], v[130:131], v[162:163]
	v_cvt_pk_bf16_f32 v184, v128, v129
	v_cvt_pk_bf16_f32 v185, v130, v131
	global_store_dwordx2 v121, v[184:185], s[12:13]
	v_pk_add_f32 v[148:149], v[148:149], 1.0 op_sel_hi:[1,0]
	v_pk_add_f32 v[150:151], v[150:151], 1.0 op_sel_hi:[1,0]
	v_pk_mul_f32 v[148:149], v[104:105], v[148:149]
	v_pk_mul_f32 v[150:151], v[106:107], v[150:151]
	v_pk_mul_f32 v[132:133], v[132:133], v[210:211] op_sel_hi:[1,0]
	v_pk_mul_f32 v[134:135], v[134:135], v[210:211] op_sel_hi:[1,0]
	v_pk_fma_f32 v[132:133], v[148:149], v[132:133], v[164:165]
	v_pk_fma_f32 v[134:135], v[150:151], v[134:135], v[166:167]
	v_cvt_pk_bf16_f32 v186, v132, v133
	v_cvt_pk_bf16_f32 v187, v134, v135
	global_store_dwordx2 v121, v[186:187], s[12:13] offset:512
	v_pk_add_f32 v[152:153], v[152:153], 1.0 op_sel_hi:[1,0]
	v_pk_add_f32 v[154:155], v[154:155], 1.0 op_sel_hi:[1,0]
	v_pk_mul_f32 v[152:153], v[108:109], v[152:153]
	v_pk_mul_f32 v[154:155], v[110:111], v[154:155]
	v_pk_mul_f32 v[136:137], v[136:137], v[210:211] op_sel_hi:[1,0]
	v_pk_mul_f32 v[138:139], v[138:139], v[210:211] op_sel_hi:[1,0]
	v_pk_fma_f32 v[136:137], v[152:153], v[136:137], v[168:169]
	v_pk_fma_f32 v[138:139], v[154:155], v[138:139], v[170:171]
	v_cvt_pk_bf16_f32 v188, v136, v137
	v_cvt_pk_bf16_f32 v189, v138, v139
	global_store_dwordx2 v121, v[188:189], s[12:13] offset:1024
	v_pk_add_f32 v[156:157], v[156:157], 1.0 op_sel_hi:[1,0]
	v_pk_add_f32 v[158:159], v[158:159], 1.0 op_sel_hi:[1,0]
	v_pk_mul_f32 v[156:157], v[112:113], v[156:157]
	v_pk_mul_f32 v[158:159], v[114:115], v[158:159]
	v_pk_mul_f32 v[140:141], v[140:141], v[210:211] op_sel_hi:[1,0]
	v_pk_mul_f32 v[142:143], v[142:143], v[210:211] op_sel_hi:[1,0]
	v_pk_fma_f32 v[140:141], v[156:157], v[140:141], v[172:173]
	v_pk_fma_f32 v[142:143], v[158:159], v[142:143], v[174:175]
	v_cvt_pk_bf16_f32 v190, v140, v141
	v_cvt_pk_bf16_f32 v191, v142, v143
	global_store_dwordx2 v121, v[190:191], s[12:13] offset:1536
	s_add_u32 s10, s10, 0x400000
	s_addc_u32 s11, s11, 0
	s_add_u32 s12, s12, 0x400000
	s_addc_u32 s13, s13, 0
	s_add_u32 s4, s4, 0x800000
	s_addc_u32 s5, s5, 0
	s_add_u32 s6, s6, 0x3000
	s_addc_u32 s7, s7, 0
	s_add_u32 s8, s8, 0x3000
	s_addc_u32 s9, s9, 0
	global_load_dwordx4 v[128:131], v120, s[4:5] nt
	global_load_dwordx4 v[132:135], v120, s[4:5] offset:1024 nt
	global_load_dwordx4 v[136:139], v120, s[4:5] offset:2048 nt
	global_load_dwordx4 v[140:143], v120, s[4:5] offset:3072 nt
	global_load_dwordx4 v[144:147], v120, s[8:9]
	global_load_dwordx4 v[148:151], v120, s[8:9] offset:1024
	global_load_dwordx4 v[152:155], v120, s[8:9] offset:2048
	global_load_dwordx4 v[156:159], v120, s[8:9] offset:3072
	global_load_dwordx4 v[160:163], v120, s[6:7]
	global_load_dwordx4 v[164:167], v120, s[6:7] offset:1024
	global_load_dwordx4 v[168:171], v120, s[6:7] offset:2048
	global_load_dwordx4 v[172:175], v120, s[6:7] offset:3072
	s_waitcnt vmcnt(20)
	v_pk_add_f32 v[64:65], v[64:65], v[84:85]
	v_pk_add_f32 v[66:67], v[66:67], v[86:87]
	v_pk_add_f32 v[68:69], v[68:69], v[88:89]
	v_pk_add_f32 v[70:71], v[70:71], v[90:91]
	v_pk_add_f32 v[72:73], v[72:73], v[92:93]
	v_pk_add_f32 v[74:75], v[74:75], v[94:95]
	v_pk_add_f32 v[76:77], v[76:77], v[96:97]
	v_pk_add_f32 v[78:79], v[78:79], v[98:99]
	v_cvt_pk_bf16_f32 v176, v64, v65
	v_cvt_pk_bf16_f32 v177, v66, v67
	global_store_dwordx2 v121, v[176:177], s[10:11]
	v_cvt_pk_bf16_f32 v178, v68, v69
	v_cvt_pk_bf16_f32 v179, v70, v71
	global_store_dwordx2 v121, v[178:179], s[10:11] offset:512
	v_cvt_pk_bf16_f32 v180, v72, v73
	v_cvt_pk_bf16_f32 v181, v74, v75
	global_store_dwordx2 v121, v[180:181], s[10:11] offset:1024
	v_cvt_pk_bf16_f32 v182, v76, v77
	v_cvt_pk_bf16_f32 v183, v78, v79
	global_store_dwordx2 v121, v[182:183], s[10:11] offset:1536
	v_mul_f32_e32 v192, v65, v65
	v_mul_f32_e32 v193, v67, v67
	v_mul_f32_e32 v194, v69, v69
	v_mul_f32_e32 v195, v71, v71
	v_mul_f32_e32 v196, v73, v73
	v_mul_f32_e32 v197, v75, v75
	v_pk_mul_f32 v[198:199], v[78:79], v[78:79]
	v_pk_mul_f32 v[200:201], v[76:77], v[76:77]
	v_fmac_f32_e32 v192, v64, v64
	v_fmac_f32_e32 v193, v66, v66
	v_fmac_f32_e32 v194, v68, v68
	v_fmac_f32_e32 v195, v70, v70
	v_fmac_f32_e32 v196, v72, v72
	v_fmac_f32_e32 v197, v74, v74
	v_add_f32_e32 v202, v201, v200
	v_add_f32_e32 v203, v198, v199
	v_add_f32_e32 v192, v192, v193
	v_add_f32_e32 v193, v194, v195
	v_add_f32_e32 v194, v196, v197
	v_add_f32_e32 v192, v192, v193
	v_add_f32_e32 v202, v202, v203
	v_add_f32_e32 v193, v192, v194
	v_add_f32_e32 v202, v193, v202
	s_nop 1
	v_add_f32_dpp v202, v202, v202 quad_perm:[1,0,3,2] row_mask:0xf bank_mask:0xf bound_ctrl:1
	s_nop 1
	v_add_f32_dpp v202, v202, v202 quad_perm:[2,3,0,1] row_mask:0xf bank_mask:0xf bound_ctrl:1
	s_nop 1
	v_add_f32_dpp v202, v202, v202 row_half_mirror row_mask:0xf bank_mask:0xf bound_ctrl:1
	s_nop 1
	v_add_f32_dpp v202, v202, v202 row_mirror row_mask:0xf bank_mask:0xf bound_ctrl:1
	s_nop 1
	v_readlane_b32 s14, v202, 16
	v_readlane_b32 s15, v202, 48
	v_readlane_b32 s18, v202, 0
	v_readlane_b32 s19, v202, 32
	s_nop 1
	v_mov_b32_e32 v202, s14
	v_mov_b32_e32 v203, s15
	v_pk_add_f32 v[202:203], s[18:19], v[202:203]
	s_nop 0
	v_add_f32_e32 v202, v202, v203
	v_fmamk_f32 v202, v202, 0x3a800000, v116
	v_mul_f32_e32 v203, 0x4f800000, v202
	v_cmp_gt_f32_e32 vcc, s3, v202
	s_nop 1
	v_cndmask_b32_e32 v202, v202, v203, vcc
	v_sqrt_f32_e32 v203, v202
	s_nop 0
	v_add_u32_e32 v204, -1, v203
	v_add_u32_e32 v205, 1, v203
	v_fma_f32 v206, -v204, v203, v202
	v_fma_f32 v207, -v205, v203, v202
	v_cmp_ge_f32_e64 s[20:21], 0, v206
	s_nop 1
	v_cndmask_b32_e64 v203, v203, v204, s[20:21]
	v_cmp_lt_f32_e64 s[20:21], 0, v207
	s_nop 1
	v_cndmask_b32_e64 v203, v203, v205, s[20:21]
	v_mul_f32_e32 v204, 0x37800000, v203
	v_cndmask_b32_e32 v203, v203, v204, vcc
	v_cmp_class_f32_e32 vcc, v202, v117
	s_nop 1
	v_cndmask_b32_e32 v204, v203, v202, vcc
	v_div_scale_f32 v205, s[20:21], v204, v204, 1.0
	v_rcp_f32_e32 v206, v205
	v_div_scale_f32 v207, vcc, 1.0, v204, 1.0
	s_nop 0
	v_fma_f32 v208, -v205, v206, 1.0
	v_fmac_f32_e32 v206, v208, v206
	v_mul_f32_e32 v208, v207, v206
	v_fma_f32 v209, -v205, v208, v207
	v_fmac_f32_e32 v208, v209, v206
	v_fma_f32 v205, -v205, v208, v207
	v_div_fmas_f32 v205, v205, v206, v208
	v_div_fixup_f32 v210, v205, v204, 1.0
	v_pk_add_f32 v[16:17], v[16:17], 1.0 op_sel_hi:[1,0]
	v_pk_add_f32 v[18:19], v[18:19], 1.0 op_sel_hi:[1,0]
	v_pk_mul_f32 v[16:17], v[100:101], v[16:17]
	v_pk_mul_f32 v[18:19], v[102:103], v[18:19]
	v_pk_mul_f32 v[64:65], v[64:65], v[210:211] op_sel_hi:[1,0]
	v_pk_mul_f32 v[66:67], v[66:67], v[210:211] op_sel_hi:[1,0]
	v_pk_fma_f32 v[64:65], v[16:17], v[64:65], v[32:33]
	v_pk_fma_f32 v[66:67], v[18:19], v[66:67], v[34:35]
	v_cvt_pk_bf16_f32 v184, v64, v65
	v_cvt_pk_bf16_f32 v185, v66, v67
	global_store_dwordx2 v121, v[184:185], s[12:13]
	v_pk_add_f32 v[20:21], v[20:21], 1.0 op_sel_hi:[1,0]
	v_pk_add_f32 v[22:23], v[22:23], 1.0 op_sel_hi:[1,0]
	v_pk_mul_f32 v[20:21], v[104:105], v[20:21]
	v_pk_mul_f32 v[22:23], v[106:107], v[22:23]
	v_pk_mul_f32 v[68:69], v[68:69], v[210:211] op_sel_hi:[1,0]
	v_pk_mul_f32 v[70:71], v[70:71], v[210:211] op_sel_hi:[1,0]
	v_pk_fma_f32 v[68:69], v[20:21], v[68:69], v[36:37]
	v_pk_fma_f32 v[70:71], v[22:23], v[70:71], v[38:39]
	v_cvt_pk_bf16_f32 v186, v68, v69
	v_cvt_pk_bf16_f32 v187, v70, v71
	global_store_dwordx2 v121, v[186:187], s[12:13] offset:512
	v_pk_add_f32 v[24:25], v[24:25], 1.0 op_sel_hi:[1,0]
	v_pk_add_f32 v[26:27], v[26:27], 1.0 op_sel_hi:[1,0]
	v_pk_mul_f32 v[24:25], v[108:109], v[24:25]
	v_pk_mul_f32 v[26:27], v[110:111], v[26:27]
	v_pk_mul_f32 v[72:73], v[72:73], v[210:211] op_sel_hi:[1,0]
	v_pk_mul_f32 v[74:75], v[74:75], v[210:211] op_sel_hi:[1,0]
	v_pk_fma_f32 v[72:73], v[24:25], v[72:73], v[40:41]
	v_pk_fma_f32 v[74:75], v[26:27], v[74:75], v[42:43]
	v_cvt_pk_bf16_f32 v188, v72, v73
	v_cvt_pk_bf16_f32 v189, v74, v75
	global_store_dwordx2 v121, v[188:189], s[12:13] offset:1024
	v_pk_add_f32 v[28:29], v[28:29], 1.0 op_sel_hi:[1,0]
	v_pk_add_f32 v[30:31], v[30:31], 1.0 op_sel_hi:[1,0]
	v_pk_mul_f32 v[28:29], v[112:113], v[28:29]
	v_pk_mul_f32 v[30:31], v[114:115], v[30:31]
	v_pk_mul_f32 v[76:77], v[76:77], v[210:211] op_sel_hi:[1,0]
	v_pk_mul_f32 v[78:79], v[78:79], v[210:211] op_sel_hi:[1,0]
	v_pk_fma_f32 v[76:77], v[28:29], v[76:77], v[44:45]
	v_pk_fma_f32 v[78:79], v[30:31], v[78:79], v[46:47]
	v_cvt_pk_bf16_f32 v190, v76, v77
	v_cvt_pk_bf16_f32 v191, v78, v79
	global_store_dwordx2 v121, v[190:191], s[12:13] offset:1536
	s_add_u32 s10, s10, 0x400000
	s_addc_u32 s11, s11, 0
	s_add_u32 s12, s12, 0x400000
	s_addc_u32 s13, s13, 0
	s_add_u32 s4, s4, 0x800000
	s_addc_u32 s5, s5, 0
	s_add_u32 s6, s6, 0x3000
	s_addc_u32 s7, s7, 0
	s_add_u32 s8, s8, 0x3000
	s_addc_u32 s9, s9, 0
	global_load_dwordx4 v[64:67], v120, s[4:5] nt
	global_load_dwordx4 v[68:71], v120, s[4:5] offset:1024 nt
	global_load_dwordx4 v[72:75], v120, s[4:5] offset:2048 nt
	global_load_dwordx4 v[76:79], v120, s[4:5] offset:3072 nt
	global_load_dwordx4 v[16:19], v120, s[8:9]
	global_load_dwordx4 v[20:23], v120, s[8:9] offset:1024
	global_load_dwordx4 v[24:27], v120, s[8:9] offset:2048
	global_load_dwordx4 v[28:31], v120, s[8:9] offset:3072
	global_load_dwordx4 v[32:35], v120, s[6:7]
	global_load_dwordx4 v[36:39], v120, s[6:7] offset:1024
	global_load_dwordx4 v[40:43], v120, s[6:7] offset:2048
	global_load_dwordx4 v[44:47], v120, s[6:7] offset:3072
	s_waitcnt vmcnt(20)
	v_pk_add_f32 v[128:129], v[128:129], v[84:85]
	v_pk_add_f32 v[130:131], v[130:131], v[86:87]
	v_pk_add_f32 v[132:133], v[132:133], v[88:89]
	v_pk_add_f32 v[134:135], v[134:135], v[90:91]
	v_pk_add_f32 v[136:137], v[136:137], v[92:93]
	v_pk_add_f32 v[138:139], v[138:139], v[94:95]
	v_pk_add_f32 v[140:141], v[140:141], v[96:97]
	v_pk_add_f32 v[142:143], v[142:143], v[98:99]
	v_cvt_pk_bf16_f32 v176, v128, v129
	v_cvt_pk_bf16_f32 v177, v130, v131
	global_store_dwordx2 v121, v[176:177], s[10:11]
	v_cvt_pk_bf16_f32 v178, v132, v133
	v_cvt_pk_bf16_f32 v179, v134, v135
	global_store_dwordx2 v121, v[178:179], s[10:11] offset:512
	v_cvt_pk_bf16_f32 v180, v136, v137
	v_cvt_pk_bf16_f32 v181, v138, v139
	global_store_dwordx2 v121, v[180:181], s[10:11] offset:1024
	v_cvt_pk_bf16_f32 v182, v140, v141
	v_cvt_pk_bf16_f32 v183, v142, v143
	global_store_dwordx2 v121, v[182:183], s[10:11] offset:1536
	v_mul_f32_e32 v192, v129, v129
	v_mul_f32_e32 v193, v131, v131
	v_mul_f32_e32 v194, v133, v133
	v_mul_f32_e32 v195, v135, v135
	v_mul_f32_e32 v196, v137, v137
	v_mul_f32_e32 v197, v139, v139
	v_pk_mul_f32 v[198:199], v[142:143], v[142:143]
	v_pk_mul_f32 v[200:201], v[140:141], v[140:141]
	v_fmac_f32_e32 v192, v128, v128
	v_fmac_f32_e32 v193, v130, v130
	v_fmac_f32_e32 v194, v132, v132
	v_fmac_f32_e32 v195, v134, v134
	v_fmac_f32_e32 v196, v136, v136
	v_fmac_f32_e32 v197, v138, v138
	v_add_f32_e32 v202, v201, v200
	v_add_f32_e32 v203, v198, v199
	v_add_f32_e32 v192, v192, v193
	v_add_f32_e32 v193, v194, v195
	v_add_f32_e32 v194, v196, v197
	v_add_f32_e32 v192, v192, v193
	v_add_f32_e32 v202, v202, v203
	v_add_f32_e32 v193, v192, v194
	v_add_f32_e32 v202, v193, v202
	s_nop 1
	v_add_f32_dpp v202, v202, v202 quad_perm:[1,0,3,2] row_mask:0xf bank_mask:0xf bound_ctrl:1
	s_nop 1
	v_add_f32_dpp v202, v202, v202 quad_perm:[2,3,0,1] row_mask:0xf bank_mask:0xf bound_ctrl:1
	s_nop 1
	v_add_f32_dpp v202, v202, v202 row_half_mirror row_mask:0xf bank_mask:0xf bound_ctrl:1
	s_nop 1
	v_add_f32_dpp v202, v202, v202 row_mirror row_mask:0xf bank_mask:0xf bound_ctrl:1
	s_nop 1
	v_readlane_b32 s14, v202, 16
	v_readlane_b32 s15, v202, 48
	v_readlane_b32 s18, v202, 0
	v_readlane_b32 s19, v202, 32
	s_nop 1
	v_mov_b32_e32 v202, s14
	v_mov_b32_e32 v203, s15
	v_pk_add_f32 v[202:203], s[18:19], v[202:203]
	s_nop 0
	v_add_f32_e32 v202, v202, v203
	v_fmamk_f32 v202, v202, 0x3a800000, v116
	v_mul_f32_e32 v203, 0x4f800000, v202
	v_cmp_gt_f32_e32 vcc, s3, v202
	s_nop 1
	v_cndmask_b32_e32 v202, v202, v203, vcc
	v_sqrt_f32_e32 v203, v202
	s_nop 0
	v_add_u32_e32 v204, -1, v203
	v_add_u32_e32 v205, 1, v203
	v_fma_f32 v206, -v204, v203, v202
	v_fma_f32 v207, -v205, v203, v202
	v_cmp_ge_f32_e64 s[20:21], 0, v206
	s_nop 1
	v_cndmask_b32_e64 v203, v203, v204, s[20:21]
	v_cmp_lt_f32_e64 s[20:21], 0, v207
	s_nop 1
	v_cndmask_b32_e64 v203, v203, v205, s[20:21]
	v_mul_f32_e32 v204, 0x37800000, v203
	v_cndmask_b32_e32 v203, v203, v204, vcc
	v_cmp_class_f32_e32 vcc, v202, v117
	s_nop 1
	v_cndmask_b32_e32 v204, v203, v202, vcc
	v_div_scale_f32 v205, s[20:21], v204, v204, 1.0
	v_rcp_f32_e32 v206, v205
	v_div_scale_f32 v207, vcc, 1.0, v204, 1.0
	s_nop 0
	v_fma_f32 v208, -v205, v206, 1.0
	v_fmac_f32_e32 v206, v208, v206
	v_mul_f32_e32 v208, v207, v206
	v_fma_f32 v209, -v205, v208, v207
	v_fmac_f32_e32 v208, v209, v206
	v_fma_f32 v205, -v205, v208, v207
	v_div_fmas_f32 v205, v205, v206, v208
	v_div_fixup_f32 v210, v205, v204, 1.0
	v_pk_add_f32 v[144:145], v[144:145], 1.0 op_sel_hi:[1,0]
	v_pk_add_f32 v[146:147], v[146:147], 1.0 op_sel_hi:[1,0]
	v_pk_mul_f32 v[144:145], v[100:101], v[144:145]
	v_pk_mul_f32 v[146:147], v[102:103], v[146:147]
	v_pk_mul_f32 v[128:129], v[128:129], v[210:211] op_sel_hi:[1,0]
	v_pk_mul_f32 v[130:131], v[130:131], v[210:211] op_sel_hi:[1,0]
	v_pk_fma_f32 v[128:129], v[144:145], v[128:129], v[160:161]
	v_pk_fma_f32 v[130:131], v[146:147], v[130:131], v[162:163]
	v_cvt_pk_bf16_f32 v184, v128, v129
	v_cvt_pk_bf16_f32 v185, v130, v131
	global_store_dwordx2 v121, v[184:185], s[12:13]
	v_pk_add_f32 v[148:149], v[148:149], 1.0 op_sel_hi:[1,0]
	v_pk_add_f32 v[150:151], v[150:151], 1.0 op_sel_hi:[1,0]
	v_pk_mul_f32 v[148:149], v[104:105], v[148:149]
	v_pk_mul_f32 v[150:151], v[106:107], v[150:151]
	v_pk_mul_f32 v[132:133], v[132:133], v[210:211] op_sel_hi:[1,0]
	v_pk_mul_f32 v[134:135], v[134:135], v[210:211] op_sel_hi:[1,0]
	v_pk_fma_f32 v[132:133], v[148:149], v[132:133], v[164:165]
	v_pk_fma_f32 v[134:135], v[150:151], v[134:135], v[166:167]
	v_cvt_pk_bf16_f32 v186, v132, v133
	v_cvt_pk_bf16_f32 v187, v134, v135
	global_store_dwordx2 v121, v[186:187], s[12:13] offset:512
	v_pk_add_f32 v[152:153], v[152:153], 1.0 op_sel_hi:[1,0]
	v_pk_add_f32 v[154:155], v[154:155], 1.0 op_sel_hi:[1,0]
	v_pk_mul_f32 v[152:153], v[108:109], v[152:153]
	v_pk_mul_f32 v[154:155], v[110:111], v[154:155]
	v_pk_mul_f32 v[136:137], v[136:137], v[210:211] op_sel_hi:[1,0]
	v_pk_mul_f32 v[138:139], v[138:139], v[210:211] op_sel_hi:[1,0]
	v_pk_fma_f32 v[136:137], v[152:153], v[136:137], v[168:169]
	v_pk_fma_f32 v[138:139], v[154:155], v[138:139], v[170:171]
	v_cvt_pk_bf16_f32 v188, v136, v137
	v_cvt_pk_bf16_f32 v189, v138, v139
	global_store_dwordx2 v121, v[188:189], s[12:13] offset:1024
	v_pk_add_f32 v[156:157], v[156:157], 1.0 op_sel_hi:[1,0]
	v_pk_add_f32 v[158:159], v[158:159], 1.0 op_sel_hi:[1,0]
	v_pk_mul_f32 v[156:157], v[112:113], v[156:157]
	v_pk_mul_f32 v[158:159], v[114:115], v[158:159]
	v_pk_mul_f32 v[140:141], v[140:141], v[210:211] op_sel_hi:[1,0]
	v_pk_mul_f32 v[142:143], v[142:143], v[210:211] op_sel_hi:[1,0]
	v_pk_fma_f32 v[140:141], v[156:157], v[140:141], v[172:173]
	v_pk_fma_f32 v[142:143], v[158:159], v[142:143], v[174:175]
	v_cvt_pk_bf16_f32 v190, v140, v141
	v_cvt_pk_bf16_f32 v191, v142, v143
	global_store_dwordx2 v121, v[190:191], s[12:13] offset:1536
	s_add_u32 s10, s10, 0x400000
	s_addc_u32 s11, s11, 0
	s_add_u32 s12, s12, 0x400000
	s_addc_u32 s13, s13, 0
	s_add_u32 s4, s4, 0x800000
	s_addc_u32 s5, s5, 0
	s_add_u32 s6, s6, 0x3000
	s_addc_u32 s7, s7, 0
	s_add_u32 s8, s8, 0x3000
	s_addc_u32 s9, s9, 0
	global_load_dwordx4 v[128:131], v120, s[4:5] nt
	global_load_dwordx4 v[132:135], v120, s[4:5] offset:1024 nt
	global_load_dwordx4 v[136:139], v120, s[4:5] offset:2048 nt
	global_load_dwordx4 v[140:143], v120, s[4:5] offset:3072 nt
	global_load_dwordx4 v[144:147], v120, s[8:9]
	global_load_dwordx4 v[148:151], v120, s[8:9] offset:1024
	global_load_dwordx4 v[152:155], v120, s[8:9] offset:2048
	global_load_dwordx4 v[156:159], v120, s[8:9] offset:3072
	global_load_dwordx4 v[160:163], v120, s[6:7]
	global_load_dwordx4 v[164:167], v120, s[6:7] offset:1024
	global_load_dwordx4 v[168:171], v120, s[6:7] offset:2048
	global_load_dwordx4 v[172:175], v120, s[6:7] offset:3072
	s_waitcnt vmcnt(20)
	v_pk_add_f32 v[64:65], v[64:65], v[84:85]
	v_pk_add_f32 v[66:67], v[66:67], v[86:87]
	v_pk_add_f32 v[68:69], v[68:69], v[88:89]
	v_pk_add_f32 v[70:71], v[70:71], v[90:91]
	v_pk_add_f32 v[72:73], v[72:73], v[92:93]
	v_pk_add_f32 v[74:75], v[74:75], v[94:95]
	v_pk_add_f32 v[76:77], v[76:77], v[96:97]
	v_pk_add_f32 v[78:79], v[78:79], v[98:99]
	v_cvt_pk_bf16_f32 v176, v64, v65
	v_cvt_pk_bf16_f32 v177, v66, v67
	global_store_dwordx2 v121, v[176:177], s[10:11]
	v_cvt_pk_bf16_f32 v178, v68, v69
	v_cvt_pk_bf16_f32 v179, v70, v71
	global_store_dwordx2 v121, v[178:179], s[10:11] offset:512
	v_cvt_pk_bf16_f32 v180, v72, v73
	v_cvt_pk_bf16_f32 v181, v74, v75
	global_store_dwordx2 v121, v[180:181], s[10:11] offset:1024
	v_cvt_pk_bf16_f32 v182, v76, v77
	v_cvt_pk_bf16_f32 v183, v78, v79
	global_store_dwordx2 v121, v[182:183], s[10:11] offset:1536
	v_mul_f32_e32 v192, v65, v65
	v_mul_f32_e32 v193, v67, v67
	v_mul_f32_e32 v194, v69, v69
	v_mul_f32_e32 v195, v71, v71
	v_mul_f32_e32 v196, v73, v73
	v_mul_f32_e32 v197, v75, v75
	v_pk_mul_f32 v[198:199], v[78:79], v[78:79]
	v_pk_mul_f32 v[200:201], v[76:77], v[76:77]
	v_fmac_f32_e32 v192, v64, v64
	v_fmac_f32_e32 v193, v66, v66
	v_fmac_f32_e32 v194, v68, v68
	v_fmac_f32_e32 v195, v70, v70
	v_fmac_f32_e32 v196, v72, v72
	v_fmac_f32_e32 v197, v74, v74
	v_add_f32_e32 v202, v201, v200
	v_add_f32_e32 v203, v198, v199
	v_add_f32_e32 v192, v192, v193
	v_add_f32_e32 v193, v194, v195
	v_add_f32_e32 v194, v196, v197
	v_add_f32_e32 v192, v192, v193
	v_add_f32_e32 v202, v202, v203
	v_add_f32_e32 v193, v192, v194
	v_add_f32_e32 v202, v193, v202
	s_nop 1
	v_add_f32_dpp v202, v202, v202 quad_perm:[1,0,3,2] row_mask:0xf bank_mask:0xf bound_ctrl:1
	s_nop 1
	v_add_f32_dpp v202, v202, v202 quad_perm:[2,3,0,1] row_mask:0xf bank_mask:0xf bound_ctrl:1
	s_nop 1
	v_add_f32_dpp v202, v202, v202 row_half_mirror row_mask:0xf bank_mask:0xf bound_ctrl:1
	s_nop 1
	v_add_f32_dpp v202, v202, v202 row_mirror row_mask:0xf bank_mask:0xf bound_ctrl:1
	s_nop 1
	v_readlane_b32 s14, v202, 16
	v_readlane_b32 s15, v202, 48
	v_readlane_b32 s18, v202, 0
	v_readlane_b32 s19, v202, 32
	s_nop 1
	v_mov_b32_e32 v202, s14
	v_mov_b32_e32 v203, s15
	v_pk_add_f32 v[202:203], s[18:19], v[202:203]
	s_nop 0
	v_add_f32_e32 v202, v202, v203
	v_fmamk_f32 v202, v202, 0x3a800000, v116
	v_mul_f32_e32 v203, 0x4f800000, v202
	v_cmp_gt_f32_e32 vcc, s3, v202
	s_nop 1
	v_cndmask_b32_e32 v202, v202, v203, vcc
	v_sqrt_f32_e32 v203, v202
	s_nop 0
	v_add_u32_e32 v204, -1, v203
	v_add_u32_e32 v205, 1, v203
	v_fma_f32 v206, -v204, v203, v202
	v_fma_f32 v207, -v205, v203, v202
	v_cmp_ge_f32_e64 s[20:21], 0, v206
	s_nop 1
	v_cndmask_b32_e64 v203, v203, v204, s[20:21]
	v_cmp_lt_f32_e64 s[20:21], 0, v207
	s_nop 1
	v_cndmask_b32_e64 v203, v203, v205, s[20:21]
	v_mul_f32_e32 v204, 0x37800000, v203
	v_cndmask_b32_e32 v203, v203, v204, vcc
	v_cmp_class_f32_e32 vcc, v202, v117
	s_nop 1
	v_cndmask_b32_e32 v204, v203, v202, vcc
	v_div_scale_f32 v205, s[20:21], v204, v204, 1.0
	v_rcp_f32_e32 v206, v205
	v_div_scale_f32 v207, vcc, 1.0, v204, 1.0
	s_nop 0
	v_fma_f32 v208, -v205, v206, 1.0
	v_fmac_f32_e32 v206, v208, v206
	v_mul_f32_e32 v208, v207, v206
	v_fma_f32 v209, -v205, v208, v207
	v_fmac_f32_e32 v208, v209, v206
	v_fma_f32 v205, -v205, v208, v207
	v_div_fmas_f32 v205, v205, v206, v208
	v_div_fixup_f32 v210, v205, v204, 1.0
	v_pk_add_f32 v[16:17], v[16:17], 1.0 op_sel_hi:[1,0]
	v_pk_add_f32 v[18:19], v[18:19], 1.0 op_sel_hi:[1,0]
	v_pk_mul_f32 v[16:17], v[100:101], v[16:17]
	v_pk_mul_f32 v[18:19], v[102:103], v[18:19]
	v_pk_mul_f32 v[64:65], v[64:65], v[210:211] op_sel_hi:[1,0]
	v_pk_mul_f32 v[66:67], v[66:67], v[210:211] op_sel_hi:[1,0]
	v_pk_fma_f32 v[64:65], v[16:17], v[64:65], v[32:33]
	v_pk_fma_f32 v[66:67], v[18:19], v[66:67], v[34:35]
	v_cvt_pk_bf16_f32 v184, v64, v65
	v_cvt_pk_bf16_f32 v185, v66, v67
	global_store_dwordx2 v121, v[184:185], s[12:13]
	v_pk_add_f32 v[20:21], v[20:21], 1.0 op_sel_hi:[1,0]
	v_pk_add_f32 v[22:23], v[22:23], 1.0 op_sel_hi:[1,0]
	v_pk_mul_f32 v[20:21], v[104:105], v[20:21]
	v_pk_mul_f32 v[22:23], v[106:107], v[22:23]
	v_pk_mul_f32 v[68:69], v[68:69], v[210:211] op_sel_hi:[1,0]
	v_pk_mul_f32 v[70:71], v[70:71], v[210:211] op_sel_hi:[1,0]
	v_pk_fma_f32 v[68:69], v[20:21], v[68:69], v[36:37]
	v_pk_fma_f32 v[70:71], v[22:23], v[70:71], v[38:39]
	v_cvt_pk_bf16_f32 v186, v68, v69
	v_cvt_pk_bf16_f32 v187, v70, v71
	global_store_dwordx2 v121, v[186:187], s[12:13] offset:512
	v_pk_add_f32 v[24:25], v[24:25], 1.0 op_sel_hi:[1,0]
	v_pk_add_f32 v[26:27], v[26:27], 1.0 op_sel_hi:[1,0]
	v_pk_mul_f32 v[24:25], v[108:109], v[24:25]
	v_pk_mul_f32 v[26:27], v[110:111], v[26:27]
	v_pk_mul_f32 v[72:73], v[72:73], v[210:211] op_sel_hi:[1,0]
	v_pk_mul_f32 v[74:75], v[74:75], v[210:211] op_sel_hi:[1,0]
	v_pk_fma_f32 v[72:73], v[24:25], v[72:73], v[40:41]
	v_pk_fma_f32 v[74:75], v[26:27], v[74:75], v[42:43]
	v_cvt_pk_bf16_f32 v188, v72, v73
	v_cvt_pk_bf16_f32 v189, v74, v75
	global_store_dwordx2 v121, v[188:189], s[12:13] offset:1024
	v_pk_add_f32 v[28:29], v[28:29], 1.0 op_sel_hi:[1,0]
	v_pk_add_f32 v[30:31], v[30:31], 1.0 op_sel_hi:[1,0]
	v_pk_mul_f32 v[28:29], v[112:113], v[28:29]
	v_pk_mul_f32 v[30:31], v[114:115], v[30:31]
	v_pk_mul_f32 v[76:77], v[76:77], v[210:211] op_sel_hi:[1,0]
	v_pk_mul_f32 v[78:79], v[78:79], v[210:211] op_sel_hi:[1,0]
	v_pk_fma_f32 v[76:77], v[28:29], v[76:77], v[44:45]
	v_pk_fma_f32 v[78:79], v[30:31], v[78:79], v[46:47]
	v_cvt_pk_bf16_f32 v190, v76, v77
	v_cvt_pk_bf16_f32 v191, v78, v79
	global_store_dwordx2 v121, v[190:191], s[12:13] offset:1536
	s_add_u32 s10, s10, 0x400000
	s_addc_u32 s11, s11, 0
	s_add_u32 s12, s12, 0x400000
	s_addc_u32 s13, s13, 0
	s_mov_b64 s[4:5], s[22:23]
	s_add_u32 s6, s6, 0x3000
	s_addc_u32 s7, s7, 0
	s_add_u32 s8, s8, 0x3000
	s_addc_u32 s9, s9, 0
	global_load_dwordx4 v[64:67], v120, s[4:5] nt
	global_load_dwordx4 v[68:71], v120, s[4:5] offset:1024 nt
	global_load_dwordx4 v[72:75], v120, s[4:5] offset:2048 nt
	global_load_dwordx4 v[76:79], v120, s[4:5] offset:3072 nt
	global_load_dwordx4 v[16:19], v120, s[8:9]
	global_load_dwordx4 v[20:23], v120, s[8:9] offset:1024
	global_load_dwordx4 v[24:27], v120, s[8:9] offset:2048
	global_load_dwordx4 v[28:31], v120, s[8:9] offset:3072
	global_load_dwordx4 v[32:35], v120, s[6:7]
	global_load_dwordx4 v[36:39], v120, s[6:7] offset:1024
	global_load_dwordx4 v[40:43], v120, s[6:7] offset:2048
	global_load_dwordx4 v[44:47], v120, s[6:7] offset:3072
	s_waitcnt vmcnt(20)
	v_pk_add_f32 v[128:129], v[128:129], v[84:85]
	v_pk_add_f32 v[130:131], v[130:131], v[86:87]
	v_pk_add_f32 v[132:133], v[132:133], v[88:89]
	v_pk_add_f32 v[134:135], v[134:135], v[90:91]
	v_pk_add_f32 v[136:137], v[136:137], v[92:93]
	v_pk_add_f32 v[138:139], v[138:139], v[94:95]
	v_pk_add_f32 v[140:141], v[140:141], v[96:97]
	v_pk_add_f32 v[142:143], v[142:143], v[98:99]
	v_cvt_pk_bf16_f32 v176, v128, v129
	v_cvt_pk_bf16_f32 v177, v130, v131
	global_store_dwordx2 v121, v[176:177], s[10:11]
	v_cvt_pk_bf16_f32 v178, v132, v133
	v_cvt_pk_bf16_f32 v179, v134, v135
	global_store_dwordx2 v121, v[178:179], s[10:11] offset:512
	v_cvt_pk_bf16_f32 v180, v136, v137
	v_cvt_pk_bf16_f32 v181, v138, v139
	global_store_dwordx2 v121, v[180:181], s[10:11] offset:1024
	v_cvt_pk_bf16_f32 v182, v140, v141
	v_cvt_pk_bf16_f32 v183, v142, v143
	global_store_dwordx2 v121, v[182:183], s[10:11] offset:1536
	v_mul_f32_e32 v192, v129, v129
	v_mul_f32_e32 v193, v131, v131
	v_mul_f32_e32 v194, v133, v133
	v_mul_f32_e32 v195, v135, v135
	v_mul_f32_e32 v196, v137, v137
	v_mul_f32_e32 v197, v139, v139
	v_pk_mul_f32 v[198:199], v[142:143], v[142:143]
	v_pk_mul_f32 v[200:201], v[140:141], v[140:141]
	v_fmac_f32_e32 v192, v128, v128
	v_fmac_f32_e32 v193, v130, v130
	v_fmac_f32_e32 v194, v132, v132
	v_fmac_f32_e32 v195, v134, v134
	v_fmac_f32_e32 v196, v136, v136
	v_fmac_f32_e32 v197, v138, v138
	v_add_f32_e32 v202, v201, v200
	v_add_f32_e32 v203, v198, v199
	v_add_f32_e32 v192, v192, v193
	v_add_f32_e32 v193, v194, v195
	v_add_f32_e32 v194, v196, v197
	v_add_f32_e32 v192, v192, v193
	v_add_f32_e32 v202, v202, v203
	v_add_f32_e32 v193, v192, v194
	v_add_f32_e32 v202, v193, v202
	s_nop 1
	v_add_f32_dpp v202, v202, v202 quad_perm:[1,0,3,2] row_mask:0xf bank_mask:0xf bound_ctrl:1
	s_nop 1
	v_add_f32_dpp v202, v202, v202 quad_perm:[2,3,0,1] row_mask:0xf bank_mask:0xf bound_ctrl:1
	s_nop 1
	v_add_f32_dpp v202, v202, v202 row_half_mirror row_mask:0xf bank_mask:0xf bound_ctrl:1
	s_nop 1
	v_add_f32_dpp v202, v202, v202 row_mirror row_mask:0xf bank_mask:0xf bound_ctrl:1
	s_nop 1
	v_readlane_b32 s14, v202, 16
	v_readlane_b32 s15, v202, 48
	v_readlane_b32 s18, v202, 0
	v_readlane_b32 s19, v202, 32
	s_nop 1
	v_mov_b32_e32 v202, s14
	v_mov_b32_e32 v203, s15
	v_pk_add_f32 v[202:203], s[18:19], v[202:203]
	s_nop 0
	v_add_f32_e32 v202, v202, v203
	v_fmamk_f32 v202, v202, 0x3a800000, v116
	v_mul_f32_e32 v203, 0x4f800000, v202
	v_cmp_gt_f32_e32 vcc, s3, v202
	s_nop 1
	v_cndmask_b32_e32 v202, v202, v203, vcc
	v_sqrt_f32_e32 v203, v202
	s_nop 0
	v_add_u32_e32 v204, -1, v203
	v_add_u32_e32 v205, 1, v203
	v_fma_f32 v206, -v204, v203, v202
	v_fma_f32 v207, -v205, v203, v202
	v_cmp_ge_f32_e64 s[20:21], 0, v206
	s_nop 1
	v_cndmask_b32_e64 v203, v203, v204, s[20:21]
	v_cmp_lt_f32_e64 s[20:21], 0, v207
	s_nop 1
	v_cndmask_b32_e64 v203, v203, v205, s[20:21]
	v_mul_f32_e32 v204, 0x37800000, v203
	v_cndmask_b32_e32 v203, v203, v204, vcc
	v_cmp_class_f32_e32 vcc, v202, v117
	s_nop 1
	v_cndmask_b32_e32 v204, v203, v202, vcc
	v_div_scale_f32 v205, s[20:21], v204, v204, 1.0
	v_rcp_f32_e32 v206, v205
	v_div_scale_f32 v207, vcc, 1.0, v204, 1.0
	s_nop 0
	v_fma_f32 v208, -v205, v206, 1.0
	v_fmac_f32_e32 v206, v208, v206
	v_mul_f32_e32 v208, v207, v206
	v_fma_f32 v209, -v205, v208, v207
	v_fmac_f32_e32 v208, v209, v206
	v_fma_f32 v205, -v205, v208, v207
	v_div_fmas_f32 v205, v205, v206, v208
	v_div_fixup_f32 v210, v205, v204, 1.0
	v_pk_add_f32 v[144:145], v[144:145], 1.0 op_sel_hi:[1,0]
	v_pk_add_f32 v[146:147], v[146:147], 1.0 op_sel_hi:[1,0]
	v_pk_mul_f32 v[144:145], v[100:101], v[144:145]
	v_pk_mul_f32 v[146:147], v[102:103], v[146:147]
	v_pk_mul_f32 v[128:129], v[128:129], v[210:211] op_sel_hi:[1,0]
	v_pk_mul_f32 v[130:131], v[130:131], v[210:211] op_sel_hi:[1,0]
	v_pk_fma_f32 v[128:129], v[144:145], v[128:129], v[160:161]
	v_pk_fma_f32 v[130:131], v[146:147], v[130:131], v[162:163]
	v_cvt_pk_bf16_f32 v184, v128, v129
	v_cvt_pk_bf16_f32 v185, v130, v131
	global_store_dwordx2 v121, v[184:185], s[12:13]
	v_pk_add_f32 v[148:149], v[148:149], 1.0 op_sel_hi:[1,0]
	v_pk_add_f32 v[150:151], v[150:151], 1.0 op_sel_hi:[1,0]
	v_pk_mul_f32 v[148:149], v[104:105], v[148:149]
	v_pk_mul_f32 v[150:151], v[106:107], v[150:151]
	v_pk_mul_f32 v[132:133], v[132:133], v[210:211] op_sel_hi:[1,0]
	v_pk_mul_f32 v[134:135], v[134:135], v[210:211] op_sel_hi:[1,0]
	v_pk_fma_f32 v[132:133], v[148:149], v[132:133], v[164:165]
	v_pk_fma_f32 v[134:135], v[150:151], v[134:135], v[166:167]
	v_cvt_pk_bf16_f32 v186, v132, v133
	v_cvt_pk_bf16_f32 v187, v134, v135
	global_store_dwordx2 v121, v[186:187], s[12:13] offset:512
	v_pk_add_f32 v[152:153], v[152:153], 1.0 op_sel_hi:[1,0]
	v_pk_add_f32 v[154:155], v[154:155], 1.0 op_sel_hi:[1,0]
	v_pk_mul_f32 v[152:153], v[108:109], v[152:153]
	v_pk_mul_f32 v[154:155], v[110:111], v[154:155]
	v_pk_mul_f32 v[136:137], v[136:137], v[210:211] op_sel_hi:[1,0]
	v_pk_mul_f32 v[138:139], v[138:139], v[210:211] op_sel_hi:[1,0]
	v_pk_fma_f32 v[136:137], v[152:153], v[136:137], v[168:169]
	v_pk_fma_f32 v[138:139], v[154:155], v[138:139], v[170:171]
	v_cvt_pk_bf16_f32 v188, v136, v137
	v_cvt_pk_bf16_f32 v189, v138, v139
	global_store_dwordx2 v121, v[188:189], s[12:13] offset:1024
	v_pk_add_f32 v[156:157], v[156:157], 1.0 op_sel_hi:[1,0]
	v_pk_add_f32 v[158:159], v[158:159], 1.0 op_sel_hi:[1,0]
	v_pk_mul_f32 v[156:157], v[112:113], v[156:157]
	v_pk_mul_f32 v[158:159], v[114:115], v[158:159]
	v_pk_mul_f32 v[140:141], v[140:141], v[210:211] op_sel_hi:[1,0]
	v_pk_mul_f32 v[142:143], v[142:143], v[210:211] op_sel_hi:[1,0]
	v_pk_fma_f32 v[140:141], v[156:157], v[140:141], v[172:173]
	v_pk_fma_f32 v[142:143], v[158:159], v[142:143], v[174:175]
	v_cvt_pk_bf16_f32 v190, v140, v141
	v_cvt_pk_bf16_f32 v191, v142, v143
	global_store_dwordx2 v121, v[190:191], s[12:13] offset:1536
	s_add_u32 s10, s10, 0x400000
	s_addc_u32 s11, s11, 0
	s_add_u32 s12, s12, 0x400000
	s_addc_u32 s13, s13, 0
	s_waitcnt vmcnt(8)
	v_cvt_pk_bf16_f32 v176, v64, v65
	v_cvt_pk_bf16_f32 v177, v66, v67
	global_store_dwordx2 v121, v[176:177], s[10:11]
	v_cvt_pk_bf16_f32 v178, v68, v69
	v_cvt_pk_bf16_f32 v179, v70, v71
	global_store_dwordx2 v121, v[178:179], s[10:11] offset:512
	v_cvt_pk_bf16_f32 v180, v72, v73
	v_cvt_pk_bf16_f32 v181, v74, v75
	global_store_dwordx2 v121, v[180:181], s[10:11] offset:1024
	v_cvt_pk_bf16_f32 v182, v76, v77
	v_cvt_pk_bf16_f32 v183, v78, v79
	global_store_dwordx2 v121, v[182:183], s[10:11] offset:1536
	v_mul_f32_e32 v192, v65, v65
	v_mul_f32_e32 v193, v67, v67
	v_mul_f32_e32 v194, v69, v69
	v_mul_f32_e32 v195, v71, v71
	v_mul_f32_e32 v196, v73, v73
	v_mul_f32_e32 v197, v75, v75
	v_pk_mul_f32 v[198:199], v[78:79], v[78:79]
	v_pk_mul_f32 v[200:201], v[76:77], v[76:77]
	v_fmac_f32_e32 v192, v64, v64
	v_fmac_f32_e32 v193, v66, v66
	v_fmac_f32_e32 v194, v68, v68
	v_fmac_f32_e32 v195, v70, v70
	v_fmac_f32_e32 v196, v72, v72
	v_fmac_f32_e32 v197, v74, v74
	v_add_f32_e32 v202, v201, v200
	v_add_f32_e32 v203, v198, v199
	v_add_f32_e32 v192, v192, v193
	v_add_f32_e32 v193, v194, v195
	v_add_f32_e32 v194, v196, v197
	v_add_f32_e32 v192, v192, v193
	v_add_f32_e32 v202, v202, v203
	v_add_f32_e32 v193, v192, v194
	v_add_f32_e32 v202, v193, v202
	s_nop 1
	v_add_f32_dpp v202, v202, v202 quad_perm:[1,0,3,2] row_mask:0xf bank_mask:0xf bound_ctrl:1
	s_nop 1
	v_add_f32_dpp v202, v202, v202 quad_perm:[2,3,0,1] row_mask:0xf bank_mask:0xf bound_ctrl:1
	s_nop 1
	v_add_f32_dpp v202, v202, v202 row_half_mirror row_mask:0xf bank_mask:0xf bound_ctrl:1
	s_nop 1
	v_add_f32_dpp v202, v202, v202 row_mirror row_mask:0xf bank_mask:0xf bound_ctrl:1
	s_nop 1
	v_readlane_b32 s14, v202, 16
	v_readlane_b32 s15, v202, 48
	v_readlane_b32 s18, v202, 0
	v_readlane_b32 s19, v202, 32
	s_nop 1
	v_mov_b32_e32 v202, s14
	v_mov_b32_e32 v203, s15
	v_pk_add_f32 v[202:203], s[18:19], v[202:203]
	s_nop 0
	v_add_f32_e32 v202, v202, v203
	v_fmamk_f32 v202, v202, 0x3a800000, v116
	v_mul_f32_e32 v203, 0x4f800000, v202
	v_cmp_gt_f32_e32 vcc, s3, v202
	s_nop 1
	v_cndmask_b32_e32 v202, v202, v203, vcc
	v_sqrt_f32_e32 v203, v202
	s_nop 0
	v_add_u32_e32 v204, -1, v203
	v_add_u32_e32 v205, 1, v203
	v_fma_f32 v206, -v204, v203, v202
	v_fma_f32 v207, -v205, v203, v202
	v_cmp_ge_f32_e64 s[20:21], 0, v206
	s_nop 1
	v_cndmask_b32_e64 v203, v203, v204, s[20:21]
	v_cmp_lt_f32_e64 s[20:21], 0, v207
	s_nop 1
	v_cndmask_b32_e64 v203, v203, v205, s[20:21]
	v_mul_f32_e32 v204, 0x37800000, v203
	v_cndmask_b32_e32 v203, v203, v204, vcc
	v_cmp_class_f32_e32 vcc, v202, v117
	s_nop 1
	v_cndmask_b32_e32 v204, v203, v202, vcc
	v_div_scale_f32 v205, s[20:21], v204, v204, 1.0
	v_rcp_f32_e32 v206, v205
	v_div_scale_f32 v207, vcc, 1.0, v204, 1.0
	s_nop 0
	v_fma_f32 v208, -v205, v206, 1.0
	v_fmac_f32_e32 v206, v208, v206
	v_mul_f32_e32 v208, v207, v206
	v_fma_f32 v209, -v205, v208, v207
	v_fmac_f32_e32 v208, v209, v206
	v_fma_f32 v205, -v205, v208, v207
	v_div_fmas_f32 v205, v205, v206, v208
	v_div_fixup_f32 v210, v205, v204, 1.0
	v_pk_add_f32 v[16:17], v[16:17], 1.0 op_sel_hi:[1,0]
	v_pk_add_f32 v[18:19], v[18:19], 1.0 op_sel_hi:[1,0]
	v_pk_mul_f32 v[16:17], v[100:101], v[16:17]
	v_pk_mul_f32 v[18:19], v[102:103], v[18:19]
	v_pk_mul_f32 v[64:65], v[64:65], v[210:211] op_sel_hi:[1,0]
	v_pk_mul_f32 v[66:67], v[66:67], v[210:211] op_sel_hi:[1,0]
	v_pk_fma_f32 v[64:65], v[16:17], v[64:65], v[32:33]
	v_pk_fma_f32 v[66:67], v[18:19], v[66:67], v[34:35]
	v_cvt_pk_bf16_f32 v184, v64, v65
	v_cvt_pk_bf16_f32 v185, v66, v67
	global_store_dwordx2 v121, v[184:185], s[12:13]
	v_pk_add_f32 v[20:21], v[20:21], 1.0 op_sel_hi:[1,0]
	v_pk_add_f32 v[22:23], v[22:23], 1.0 op_sel_hi:[1,0]
	v_pk_mul_f32 v[20:21], v[104:105], v[20:21]
	v_pk_mul_f32 v[22:23], v[106:107], v[22:23]
	v_pk_mul_f32 v[68:69], v[68:69], v[210:211] op_sel_hi:[1,0]
	v_pk_mul_f32 v[70:71], v[70:71], v[210:211] op_sel_hi:[1,0]
	v_pk_fma_f32 v[68:69], v[20:21], v[68:69], v[36:37]
	v_pk_fma_f32 v[70:71], v[22:23], v[70:71], v[38:39]
	v_cvt_pk_bf16_f32 v186, v68, v69
	v_cvt_pk_bf16_f32 v187, v70, v71
	global_store_dwordx2 v121, v[186:187], s[12:13] offset:512
	v_pk_add_f32 v[24:25], v[24:25], 1.0 op_sel_hi:[1,0]
	v_pk_add_f32 v[26:27], v[26:27], 1.0 op_sel_hi:[1,0]
	v_pk_mul_f32 v[24:25], v[108:109], v[24:25]
	v_pk_mul_f32 v[26:27], v[110:111], v[26:27]
	v_pk_mul_f32 v[72:73], v[72:73], v[210:211] op_sel_hi:[1,0]
	v_pk_mul_f32 v[74:75], v[74:75], v[210:211] op_sel_hi:[1,0]
	v_pk_fma_f32 v[72:73], v[24:25], v[72:73], v[40:41]
	v_pk_fma_f32 v[74:75], v[26:27], v[74:75], v[42:43]
	v_cvt_pk_bf16_f32 v188, v72, v73
	v_cvt_pk_bf16_f32 v189, v74, v75
	global_store_dwordx2 v121, v[188:189], s[12:13] offset:1024
	v_pk_add_f32 v[28:29], v[28:29], 1.0 op_sel_hi:[1,0]
	v_pk_add_f32 v[30:31], v[30:31], 1.0 op_sel_hi:[1,0]
	v_pk_mul_f32 v[28:29], v[112:113], v[28:29]
	v_pk_mul_f32 v[30:31], v[114:115], v[30:31]
	v_pk_mul_f32 v[76:77], v[76:77], v[210:211] op_sel_hi:[1,0]
	v_pk_mul_f32 v[78:79], v[78:79], v[210:211] op_sel_hi:[1,0]
	v_pk_fma_f32 v[76:77], v[28:29], v[76:77], v[44:45]
	v_pk_fma_f32 v[78:79], v[30:31], v[78:79], v[46:47]
	v_cvt_pk_bf16_f32 v190, v76, v77
	v_cvt_pk_bf16_f32 v191, v78, v79
	global_store_dwordx2 v121, v[190:191], s[12:13] offset:1536

.LBB0_515:
	s_andn2_b64 vcc, exec, s[26:27]
	s_cbranch_vccnz .LBB0_536
	s_mov_b64 s[26:27], -1
	s_and_b64 vcc, exec, s[34:35]
	s_cbranch_vccz .LBB0_534
	v_readlane_b32 s4, v254, 60
	v_readlane_b32 s5, v254, 61
	s_and_b64 vcc, exec, s[4:5]
	s_cbranch_vccz .LBB0_531
	v_readlane_b32 s4, v254, 62
	v_readlane_b32 s5, v254, 63
	s_and_b64 vcc, exec, s[4:5]
	s_cbranch_vccz .LBB0_528
	s_and_b32 s5, s38, 1
	s_lshl_b32 s5, s5, 1
	s_cmp_eq_u32 s40, 0
	s_cselect_b32 s64, 1, 3
	s_cmp_eq_u32 s40, 1
	s_cselect_b32 s64, s5, s64
	s_sub_i32 s5, 2, s5
	s_cmp_eq_u32 s40, 2
	s_cselect_b32 s64, s5, s64

.LBB0_528:
	s_and_b64 vcc, exec, s[26:27]
	s_mov_b32 s4, s22
	s_cbranch_vccz .LBB0_530
	s_bitcmp1_b32 s38, 0
	s_cbranch_scc1 .Lsched_cppl
	s_cmp_eq_u32 s40, 1
	s_cselect_b32 s4, 0, 2
	s_cmp_lg_u32 s40, 0
	s_cselect_b32 s64, s4, 1
	v_readlane_b32 s4, v255, 0
	s_add_i32 s4, s4, s40
	s_cmp_lt_u32 s40, 2
	s_cselect_b32 s4, s22, s4
	s_branch .LBB0_530
.Lsched_cppl:
	s_cmp_eq_u32 s40, 3
	s_cselect_b32 s4, 0, 2
	s_cmp_lg_u32 s40, 0
	s_cselect_b32 s64, s4, 1
	v_readlane_b32 s5, v255, 0
	s_nop 0
	s_add_i32 s5, s5, s40
	s_add_i32 s5, s5, 1
	s_cmp_eq_u32 s40, 0
	s_cselect_b32 s4, s22, s5
	s_cmp_eq_u32 s40, 3
	s_cselect_b32 s4, s22, s4

.LBB0_849:
	v_mul_f32_e32 v130, v125, v125
	v_mul_f32_e32 v131, v127, v127
	v_fmac_f32_e32 v130, v124, v124
	v_fmac_f32_e32 v131, v126, v126
	v_add_f32_e32 v130, v130, v131
	v_mul_f32_e32 v131, v121, v121
	v_mul_f32_e32 v132, v123, v123
	v_fmac_f32_e32 v131, v120, v120
	v_fmac_f32_e32 v132, v122, v122
	v_add_f32_e32 v131, v131, v132
	v_add_f32_e32 v130, v131, v130
	v_mul_f32_e32 v131, v117, v117
	v_mul_f32_e32 v132, v119, v119
	v_fmac_f32_e32 v131, v116, v116
	v_fmac_f32_e32 v132, v118, v118
	v_add_f32_e32 v131, v131, v132
	v_add_f32_e32 v130, v131, v130
	v_mul_f32_e32 v131, v109, v109
	v_mul_f32_e32 v132, v111, v111
	v_fmac_f32_e32 v131, v108, v108
	v_fmac_f32_e32 v132, v110, v110
	v_add_f32_e32 v131, v131, v132
	v_add_f32_e32 v130, v131, v130
	v_and_b32_e32 v161, 63, v129
	v_mov_b32_e32 v131, v130
	v_mov_b32_e32 v132, v130
	s_nop 1
	v_permlane16_swap_b32_e32 v131, v132
	s_lshl_b32 s26, s64, 2
	s_add_i32 s28, s26, 0
	v_cmp_gt_u32_e32 vcc, 16, v161
	s_waitcnt lgkmcnt(0)
	v_add_f32_e32 v130, v131, v132
	v_mov_b32_e32 v131, v130
	v_mov_b32_e32 v132, v130
	s_nop 1
	v_permlane32_swap_b32_e32 v131, v132
	s_and_saveexec_b64 s[26:27], vcc
	s_cbranch_execz .LBB0_851
	s_lshl_b32 s29, s23, 10
	s_add_i32 s29, s28, s29
	s_waitcnt lgkmcnt(0)
	v_add_f32_e32 v130, v131, v132
	v_lshl_add_u32 v131, v163, 4, s29
	ds_write_b32 v131, v130
.LBB0_851:
	s_or_b64 exec, exec, s[26:27]
	v_mul_f32_e32 v130, v113, v113
	s_waitcnt lgkmcnt(0)
	v_mul_f32_e32 v131, v115, v115
	v_fmac_f32_e32 v130, v112, v112
	v_fmac_f32_e32 v131, v114, v114
	v_add_f32_e32 v130, v130, v131
	v_mul_f32_e32 v131, v105, v105
	v_mul_f32_e32 v132, v107, v107
	v_fmac_f32_e32 v131, v104, v104
	v_fmac_f32_e32 v132, v106, v106
	v_add_f32_e32 v131, v131, v132
	v_add_f32_e32 v130, v131, v130
	v_mul_f32_e32 v131, v101, v101
	v_mul_f32_e32 v132, v103, v103
	v_fmac_f32_e32 v131, v100, v100
	v_fmac_f32_e32 v132, v102, v102
	v_add_f32_e32 v131, v131, v132
	v_add_f32_e32 v130, v131, v130
	v_mul_f32_e32 v131, v97, v97
	v_mul_f32_e32 v132, v99, v99
	v_fmac_f32_e32 v131, v96, v96
	v_fmac_f32_e32 v132, v98, v98
	v_add_f32_e32 v131, v131, v132
	v_add_f32_e32 v130, v131, v130
	v_mov_b32_e32 v131, v130
	v_mov_b32_e32 v132, v130
	s_nop 1
	v_permlane16_swap_b32_e32 v131, v132
	s_waitcnt lgkmcnt(0)
	v_add_f32_e32 v130, v131, v132
	v_mov_b32_e32 v131, v130
	v_mov_b32_e32 v132, v130
	s_nop 1
	v_permlane32_swap_b32_e32 v131, v132
	s_and_saveexec_b64 s[26:27], vcc
	s_cbranch_execz .LBB0_853
	s_lshl_b32 s29, s23, 10
	s_add_i32 s29, s28, s29
	s_waitcnt lgkmcnt(0)
	v_add_f32_e32 v130, v131, v132
	v_lshl_add_u32 v131, v163, 4, s29
	ds_write_b32 v131, v130 offset:256
.LBB0_853:
	s_or_b64 exec, exec, s[26:27]
	v_mul_f32_e32 v130, v93, v93
	s_waitcnt lgkmcnt(0)
	v_mul_f32_e32 v131, v95, v95
	v_fmac_f32_e32 v130, v92, v92
	v_fmac_f32_e32 v131, v94, v94
	v_add_f32_e32 v130, v130, v131
	v_mul_f32_e32 v131, v89, v89
	v_mul_f32_e32 v132, v91, v91
	v_fmac_f32_e32 v131, v88, v88
	v_fmac_f32_e32 v132, v90, v90
	v_add_f32_e32 v131, v131, v132
	v_add_f32_e32 v130, v131, v130
	v_mul_f32_e32 v131, v85, v85
	v_mul_f32_e32 v132, v87, v87
	v_fmac_f32_e32 v131, v84, v84
	v_fmac_f32_e32 v132, v86, v86
	v_add_f32_e32 v131, v131, v132
	v_add_f32_e32 v130, v131, v130
	v_mul_f32_e32 v131, v81, v81
	v_mul_f32_e32 v132, v83, v83
	v_fmac_f32_e32 v131, v80, v80
	v_fmac_f32_e32 v132, v82, v82
	v_add_f32_e32 v131, v131, v132
	v_add_f32_e32 v130, v131, v130
	v_mov_b32_e32 v131, v130
	v_mov_b32_e32 v132, v130
	s_nop 1
	v_permlane16_swap_b32_e32 v131, v132
	s_waitcnt lgkmcnt(0)
	v_add_f32_e32 v130, v131, v132
	v_mov_b32_e32 v131, v130
	v_mov_b32_e32 v132, v130
	s_nop 1
	v_permlane32_swap_b32_e32 v131, v132
	s_and_saveexec_b64 s[26:27], vcc
	s_cbranch_execz .LBB0_855
	s_lshl_b32 s29, s23, 10
	s_add_i32 s29, s28, s29
	s_waitcnt lgkmcnt(0)
	v_add_f32_e32 v130, v131, v132
	v_lshl_add_u32 v131, v163, 4, s29
	ds_write_b32 v131, v130 offset:512
.LBB0_855:
	s_or_b64 exec, exec, s[26:27]
	v_mul_f32_e32 v130, v77, v77
	s_waitcnt lgkmcnt(0)
	v_mul_f32_e32 v131, v79, v79
	v_fmac_f32_e32 v130, v76, v76
	v_fmac_f32_e32 v131, v78, v78
	v_add_f32_e32 v130, v130, v131
	v_mul_f32_e32 v131, v73, v73
	v_mul_f32_e32 v132, v75, v75
	v_fmac_f32_e32 v131, v72, v72
	v_fmac_f32_e32 v132, v74, v74
	v_add_f32_e32 v131, v131, v132
	v_add_f32_e32 v130, v131, v130
	v_mul_f32_e32 v131, v69, v69
	v_mul_f32_e32 v132, v71, v71
	v_fmac_f32_e32 v131, v68, v68
	v_fmac_f32_e32 v132, v70, v70
	v_add_f32_e32 v131, v131, v132
	v_add_f32_e32 v130, v131, v130
	v_mul_f32_e32 v131, v65, v65
	v_mul_f32_e32 v132, v67, v67
	v_fmac_f32_e32 v131, v64, v64
	v_fmac_f32_e32 v132, v66, v66
	v_add_f32_e32 v131, v131, v132
	v_add_f32_e32 v130, v131, v130
	v_mov_b32_e32 v131, v130
	v_mov_b32_e32 v132, v130
	s_nop 1
	v_permlane16_swap_b32_e32 v131, v132
	s_waitcnt lgkmcnt(0)
	v_add_f32_e32 v130, v131, v132
	v_mov_b32_e32 v131, v130
	v_mov_b32_e32 v132, v130
	s_nop 1
	v_permlane32_swap_b32_e32 v131, v132
	s_and_saveexec_b64 s[26:27], vcc
	s_cbranch_execz .LBB0_857
	s_lshl_b32 s29, s23, 10
	s_add_i32 s29, s28, s29
	s_waitcnt lgkmcnt(0)
	v_add_f32_e32 v130, v131, v132
	v_lshl_add_u32 v131, v163, 4, s29
	ds_write_b32 v131, v130 offset:768
.LBB0_857:
	s_or_b64 exec, exec, s[26:27]
	v_mul_f32_e32 v130, v61, v61
	s_waitcnt lgkmcnt(0)
	v_mul_f32_e32 v131, v63, v63
	v_fmac_f32_e32 v130, v60, v60
	v_fmac_f32_e32 v131, v62, v62
	v_add_f32_e32 v130, v130, v131
	v_mul_f32_e32 v131, v57, v57
	v_mul_f32_e32 v132, v59, v59
	v_fmac_f32_e32 v131, v56, v56
	v_fmac_f32_e32 v132, v58, v58
	v_add_f32_e32 v131, v131, v132
	v_add_f32_e32 v130, v131, v130
	v_mul_f32_e32 v131, v53, v53
	v_mul_f32_e32 v132, v55, v55
	v_fmac_f32_e32 v131, v52, v52
	v_fmac_f32_e32 v132, v54, v54
	v_add_f32_e32 v131, v131, v132
	v_add_f32_e32 v130, v131, v130
	v_mul_f32_e32 v131, v49, v49
	v_mul_f32_e32 v132, v51, v51
	v_fmac_f32_e32 v131, v48, v48
	v_fmac_f32_e32 v132, v50, v50
	v_add_f32_e32 v131, v131, v132
	v_add_f32_e32 v130, v131, v130
	v_mov_b32_e32 v131, v130
	v_mov_b32_e32 v132, v130
	s_nop 1
	v_permlane16_swap_b32_e32 v131, v132
	s_waitcnt lgkmcnt(0)
	v_add_f32_e32 v130, v131, v132
	v_mov_b32_e32 v131, v130
	v_mov_b32_e32 v132, v130
	s_nop 1
	v_permlane32_swap_b32_e32 v131, v132
	s_and_saveexec_b64 s[26:27], vcc
	s_cbranch_execz .LBB0_859
	s_lshl_b32 s29, s23, 10
	s_add_i32 s29, s28, s29
	s_waitcnt lgkmcnt(0)
	v_add_f32_e32 v130, v131, v132
	v_lshl_add_u32 v131, v163, 4, s29
	ds_write_b32 v131, v130 offset:2048
.LBB0_859:
	s_or_b64 exec, exec, s[26:27]
	v_mul_f32_e32 v130, v45, v45
	s_waitcnt lgkmcnt(0)
	v_mul_f32_e32 v131, v47, v47
	v_fmac_f32_e32 v130, v44, v44
	v_fmac_f32_e32 v131, v46, v46
	v_add_f32_e32 v130, v130, v131
	v_mul_f32_e32 v131, v41, v41
	v_mul_f32_e32 v132, v43, v43
	v_fmac_f32_e32 v131, v40, v40
	v_fmac_f32_e32 v132, v42, v42
	v_add_f32_e32 v131, v131, v132
	v_add_f32_e32 v130, v131, v130
	v_mul_f32_e32 v131, v37, v37
	v_mul_f32_e32 v132, v39, v39
	v_fmac_f32_e32 v131, v36, v36
	v_fmac_f32_e32 v132, v38, v38
	v_add_f32_e32 v131, v131, v132
	v_add_f32_e32 v130, v131, v130
	v_mul_f32_e32 v131, v33, v33
	v_mul_f32_e32 v132, v35, v35
	v_fmac_f32_e32 v131, v32, v32
	v_fmac_f32_e32 v132, v34, v34
	v_add_f32_e32 v131, v131, v132
	v_add_f32_e32 v130, v131, v130
	v_mov_b32_e32 v131, v130
	v_mov_b32_e32 v132, v130
	s_nop 1
	v_permlane16_swap_b32_e32 v131, v132
	s_waitcnt lgkmcnt(0)
	v_add_f32_e32 v130, v131, v132
	v_mov_b32_e32 v131, v130
	v_mov_b32_e32 v132, v130
	s_nop 1
	v_permlane32_swap_b32_e32 v131, v132
	s_and_saveexec_b64 s[26:27], vcc
	s_cbranch_execz .LBB0_861
	s_lshl_b32 s29, s23, 10
	s_add_i32 s29, s28, s29
	s_waitcnt lgkmcnt(0)
	v_add_f32_e32 v130, v131, v132
	v_lshl_add_u32 v131, v163, 4, s29
	ds_write_b32 v131, v130 offset:2304
.LBB0_861:
	s_or_b64 exec, exec, s[26:27]
	v_mul_f32_e32 v130, v29, v29
	s_waitcnt lgkmcnt(0)
	v_mul_f32_e32 v131, v31, v31
	v_fmac_f32_e32 v130, v28, v28
	v_fmac_f32_e32 v131, v30, v30
	v_add_f32_e32 v130, v130, v131
	v_mul_f32_e32 v131, v25, v25
	v_mul_f32_e32 v132, v27, v27
	v_fmac_f32_e32 v131, v24, v24
	v_fmac_f32_e32 v132, v26, v26
	v_add_f32_e32 v131, v131, v132
	v_add_f32_e32 v130, v131, v130
	v_mul_f32_e32 v131, v21, v21
	v_mul_f32_e32 v132, v23, v23
	v_fmac_f32_e32 v131, v20, v20
	v_fmac_f32_e32 v132, v22, v22
	v_add_f32_e32 v131, v131, v132
	v_add_f32_e32 v130, v131, v130
	v_mul_f32_e32 v131, v17, v17
	v_mul_f32_e32 v132, v19, v19
	v_fmac_f32_e32 v131, v16, v16
	v_fmac_f32_e32 v132, v18, v18
	v_add_f32_e32 v131, v131, v132
	v_add_f32_e32 v130, v131, v130
	v_mov_b32_e32 v131, v130
	v_mov_b32_e32 v132, v130
	s_nop 1
	v_permlane16_swap_b32_e32 v131, v132
	s_waitcnt lgkmcnt(0)
	v_add_f32_e32 v130, v131, v132
	v_mov_b32_e32 v131, v130
	v_mov_b32_e32 v132, v130
	s_nop 1
	v_permlane32_swap_b32_e32 v131, v132
	s_and_saveexec_b64 s[26:27], vcc
	s_cbranch_execz .LBB0_863
	s_lshl_b32 s29, s23, 10
	s_add_i32 s29, s28, s29
	s_waitcnt lgkmcnt(0)
	v_add_f32_e32 v130, v131, v132
	v_lshl_add_u32 v131, v163, 4, s29
	ds_write_b32 v131, v130 offset:2560
.LBB0_863:
	s_or_b64 exec, exec, s[26:27]
	v_mul_f32_e32 v130, v13, v13
	s_waitcnt lgkmcnt(0)
	v_mul_f32_e32 v131, v15, v15
	v_fmac_f32_e32 v130, v12, v12
	v_fmac_f32_e32 v131, v14, v14
	v_add_f32_e32 v130, v130, v131
	v_mul_f32_e32 v131, v9, v9
	v_mul_f32_e32 v132, v11, v11
	v_fmac_f32_e32 v131, v8, v8
	v_fmac_f32_e32 v132, v10, v10
	v_add_f32_e32 v131, v131, v132
	v_add_f32_e32 v130, v131, v130
	v_mul_f32_e32 v131, v5, v5
	v_mul_f32_e32 v132, v7, v7
	v_fmac_f32_e32 v131, v4, v4
	v_fmac_f32_e32 v132, v6, v6
	v_add_f32_e32 v131, v131, v132
	v_add_f32_e32 v130, v131, v130
	v_mul_f32_e32 v131, v1, v1
	v_mul_f32_e32 v132, v3, v3
	v_fmac_f32_e32 v131, v0, v0
	v_fmac_f32_e32 v132, v2, v2
	v_add_f32_e32 v131, v131, v132
	v_add_f32_e32 v130, v131, v130
	v_mov_b32_e32 v131, v130
	v_mov_b32_e32 v132, v130
	s_nop 1
	v_permlane16_swap_b32_e32 v131, v132
	s_waitcnt lgkmcnt(0)
	v_add_f32_e32 v130, v131, v132
	v_mov_b32_e32 v131, v130
	v_mov_b32_e32 v132, v130
	s_nop 1
	v_permlane32_swap_b32_e32 v131, v132
	s_and_saveexec_b64 s[26:27], vcc
	s_cbranch_execz .LBB0_865
	s_lshl_b32 s23, s23, 10
	s_add_i32 s28, s28, s23
	s_waitcnt lgkmcnt(0)
	v_add_f32_e32 v130, v131, v132
	v_lshl_add_u32 v131, v163, 4, s28
	ds_write_b32 v131, v130 offset:2816

.LBB0_1105:
	s_barrier
	s_and_b32 s5, s68, 0xffffffc0
	v_mbcnt_lo_u32_b32 v16, -1, 0
	v_mbcnt_hi_u32_b32 v16, -1, v16
	v_mul_f32_e32 v17, v147, v147
	v_or_b32_e32 v217, s5, v16
	v_mul_f32_e32 v16, v145, v145
	v_fmac_f32_e32 v16, v144, v144
	v_fmac_f32_e32 v17, v146, v146
	v_add_f32_e32 v16, v16, v17
	v_mul_f32_e32 v17, v141, v141
	v_mul_f32_e32 v18, v143, v143
	v_fmac_f32_e32 v17, v140, v140
	v_fmac_f32_e32 v18, v142, v142
	v_add_f32_e32 v17, v17, v18
	v_add_f32_e32 v16, v17, v16
	v_mul_f32_e32 v17, v137, v137
	v_mul_f32_e32 v18, v139, v139
	v_fmac_f32_e32 v17, v136, v136
	v_fmac_f32_e32 v18, v138, v138
	v_add_f32_e32 v17, v17, v18
	v_add_f32_e32 v16, v17, v16
	v_mul_f32_e32 v17, v125, v125
	v_mul_f32_e32 v18, v127, v127
	v_fmac_f32_e32 v17, v124, v124
	v_fmac_f32_e32 v18, v126, v126
	v_add_f32_e32 v17, v17, v18
	v_add_f32_e32 v16, v17, v16
	v_and_b32_e32 v218, 63, v217
	v_mov_b32_e32 v17, v16
	v_mov_b32_e32 v18, v16
	s_nop 1
	v_permlane16_swap_b32_e32 v17, v18
	s_lshl_b32 s63, s70, 2
	v_and_b32_e32 v221, 15, v217
	s_add_i32 s59, s63, 0
	v_cmp_gt_u32_e64 s[44:45], 16, v218
	s_waitcnt lgkmcnt(0)
	v_add_f32_e32 v16, v17, v18
	v_mov_b32_e32 v17, v16
	v_mov_b32_e32 v18, v16
	s_nop 1
	v_permlane32_swap_b32_e32 v17, v18
	s_and_saveexec_b64 s[22:23], s[44:45]
	s_cbranch_execz .LBB0_1107
	s_lshl_b32 s5, s33, 10
	s_add_i32 s5, s59, s5
	s_waitcnt lgkmcnt(0)
	v_add_f32_e32 v16, v17, v18
	v_lshl_add_u32 v17, v221, 4, s5
	ds_write_b32 v17, v16
.LBB0_1107:
	s_or_b64 exec, exec, s[22:23]
	v_mul_f32_e32 v16, v133, v133
	s_waitcnt lgkmcnt(0)
	v_mul_f32_e32 v17, v135, v135
	v_fmac_f32_e32 v16, v132, v132
	v_fmac_f32_e32 v17, v134, v134
	v_add_f32_e32 v16, v16, v17
	v_mul_f32_e32 v17, v129, v129
	v_mul_f32_e32 v18, v131, v131
	v_fmac_f32_e32 v17, v128, v128
	v_fmac_f32_e32 v18, v130, v130
	v_add_f32_e32 v17, v17, v18
	v_add_f32_e32 v16, v17, v16
	v_mul_f32_e32 v17, v117, v117
	v_mul_f32_e32 v18, v119, v119
	v_fmac_f32_e32 v17, v116, v116
	v_fmac_f32_e32 v18, v118, v118
	v_add_f32_e32 v17, v17, v18
	v_add_f32_e32 v16, v17, v16
	v_mul_f32_e32 v17, v109, v109
	v_mul_f32_e32 v18, v111, v111
	v_fmac_f32_e32 v17, v108, v108
	v_fmac_f32_e32 v18, v110, v110
	v_add_f32_e32 v17, v17, v18
	v_add_f32_e32 v16, v17, v16
	v_mov_b32_e32 v17, v16
	v_mov_b32_e32 v18, v16
	s_nop 1
	v_permlane16_swap_b32_e32 v17, v18
	s_waitcnt lgkmcnt(0)
	v_add_f32_e32 v16, v17, v18
	v_mov_b32_e32 v17, v16
	v_mov_b32_e32 v18, v16
	s_nop 1
	v_permlane32_swap_b32_e32 v17, v18
	s_and_saveexec_b64 s[22:23], s[44:45]
	s_cbranch_execz .LBB0_1109
	s_lshl_b32 s5, s33, 10
	s_add_i32 s5, s59, s5
	s_waitcnt lgkmcnt(0)
	v_add_f32_e32 v16, v17, v18
	v_lshl_add_u32 v17, v221, 4, s5
	ds_write_b32 v17, v16 offset:256
.LBB0_1109:
	s_or_b64 exec, exec, s[22:23]
	v_mul_f32_e32 v16, v121, v121
	s_waitcnt lgkmcnt(0)
	v_mul_f32_e32 v17, v123, v123
	v_fmac_f32_e32 v16, v120, v120
	v_fmac_f32_e32 v17, v122, v122
	v_add_f32_e32 v16, v16, v17
	v_mul_f32_e32 v17, v113, v113
	v_mul_f32_e32 v18, v115, v115
	v_fmac_f32_e32 v17, v112, v112
	v_fmac_f32_e32 v18, v114, v114
	v_add_f32_e32 v17, v17, v18
	v_add_f32_e32 v16, v17, v16
	v_mul_f32_e32 v17, v101, v101
	v_mul_f32_e32 v18, v103, v103
	v_fmac_f32_e32 v17, v100, v100
	v_fmac_f32_e32 v18, v102, v102
	v_add_f32_e32 v17, v17, v18
	v_add_f32_e32 v16, v17, v16
	v_mul_f32_e32 v17, v93, v93
	v_mul_f32_e32 v18, v95, v95
	v_fmac_f32_e32 v17, v92, v92
	v_fmac_f32_e32 v18, v94, v94
	v_add_f32_e32 v17, v17, v18
	v_add_f32_e32 v16, v17, v16
	v_mov_b32_e32 v17, v16
	v_mov_b32_e32 v18, v16
	s_nop 1
	v_permlane16_swap_b32_e32 v17, v18
	s_waitcnt lgkmcnt(0)
	v_add_f32_e32 v16, v17, v18
	v_mov_b32_e32 v17, v16
	v_mov_b32_e32 v18, v16
	s_nop 1
	v_permlane32_swap_b32_e32 v17, v18
	s_and_saveexec_b64 s[22:23], s[44:45]
	s_cbranch_execz .LBB0_1111
	s_lshl_b32 s5, s33, 10
	s_add_i32 s5, s59, s5
	s_waitcnt lgkmcnt(0)
	v_add_f32_e32 v16, v17, v18
	v_lshl_add_u32 v17, v221, 4, s5
	ds_write_b32 v17, v16 offset:512
.LBB0_1111:
	s_or_b64 exec, exec, s[22:23]
	v_mul_f32_e32 v16, v105, v105
	s_waitcnt lgkmcnt(0)
	v_mul_f32_e32 v17, v107, v107
	v_fmac_f32_e32 v16, v104, v104
	v_fmac_f32_e32 v17, v106, v106
	v_add_f32_e32 v16, v16, v17
	v_mul_f32_e32 v17, v97, v97
	v_mul_f32_e32 v18, v99, v99
	v_fmac_f32_e32 v17, v96, v96
	v_fmac_f32_e32 v18, v98, v98
	v_add_f32_e32 v17, v17, v18
	v_add_f32_e32 v16, v17, v16
	v_mul_f32_e32 v17, v89, v89
	v_mul_f32_e32 v18, v91, v91
	v_fmac_f32_e32 v17, v88, v88
	v_fmac_f32_e32 v18, v90, v90
	v_add_f32_e32 v17, v17, v18
	v_add_f32_e32 v16, v17, v16
	v_mul_f32_e32 v17, v85, v85
	v_mul_f32_e32 v18, v87, v87
	v_fmac_f32_e32 v17, v84, v84
	v_fmac_f32_e32 v18, v86, v86
	v_add_f32_e32 v17, v17, v18
	v_add_f32_e32 v16, v17, v16
	v_mov_b32_e32 v17, v16
	v_mov_b32_e32 v18, v16
	s_nop 1
	v_permlane16_swap_b32_e32 v17, v18
	s_waitcnt lgkmcnt(0)
	v_add_f32_e32 v16, v17, v18
	v_mov_b32_e32 v17, v16
	v_mov_b32_e32 v18, v16
	s_nop 1
	v_permlane32_swap_b32_e32 v17, v18
	s_and_saveexec_b64 s[22:23], s[44:45]
	s_cbranch_execz .LBB0_1113
	s_lshl_b32 s5, s33, 10
	s_add_i32 s5, s59, s5
	s_waitcnt lgkmcnt(0)
	v_add_f32_e32 v16, v17, v18
	v_lshl_add_u32 v17, v221, 4, s5
	ds_write_b32 v17, v16 offset:768
.LBB0_1113:
	s_or_b64 exec, exec, s[22:23]
	v_mul_f32_e32 v16, v81, v81
	s_waitcnt lgkmcnt(0)
	v_mul_f32_e32 v17, v83, v83
	v_fmac_f32_e32 v16, v80, v80
	v_fmac_f32_e32 v17, v82, v82
	v_add_f32_e32 v16, v16, v17
	v_mul_f32_e32 v17, v77, v77
	v_mul_f32_e32 v18, v79, v79
	v_fmac_f32_e32 v17, v76, v76
	v_fmac_f32_e32 v18, v78, v78
	v_add_f32_e32 v17, v17, v18
	v_add_f32_e32 v16, v17, v16
	v_mul_f32_e32 v17, v69, v69
	v_mul_f32_e32 v18, v71, v71
	v_fmac_f32_e32 v17, v68, v68
	v_fmac_f32_e32 v18, v70, v70
	v_add_f32_e32 v17, v17, v18
	v_add_f32_e32 v16, v17, v16
	v_mul_f32_e32 v17, v61, v61
	v_mul_f32_e32 v18, v63, v63
	v_fmac_f32_e32 v17, v60, v60
	v_fmac_f32_e32 v18, v62, v62
	v_add_f32_e32 v17, v17, v18
	v_add_f32_e32 v16, v17, v16
	v_mov_b32_e32 v17, v16
	v_mov_b32_e32 v18, v16
	s_nop 1
	v_permlane16_swap_b32_e32 v17, v18
	s_waitcnt lgkmcnt(0)
	v_add_f32_e32 v16, v17, v18
	v_mov_b32_e32 v17, v16
	v_mov_b32_e32 v18, v16
	s_nop 1
	v_permlane32_swap_b32_e32 v17, v18
	s_and_saveexec_b64 s[22:23], s[44:45]
	s_cbranch_execz .LBB0_1115
	s_lshl_b32 s5, s33, 10
	s_add_i32 s5, s59, s5
	s_waitcnt lgkmcnt(0)
	v_add_f32_e32 v16, v17, v18
	v_lshl_add_u32 v17, v221, 4, s5
	ds_write_b32 v17, v16 offset:2048
.LBB0_1115:
	s_or_b64 exec, exec, s[22:23]
	v_mul_f32_e32 v16, v73, v73
	s_waitcnt lgkmcnt(0)
	v_mul_f32_e32 v17, v75, v75
	v_fmac_f32_e32 v16, v72, v72
	v_fmac_f32_e32 v17, v74, v74
	v_add_f32_e32 v16, v16, v17
	v_mul_f32_e32 v17, v65, v65
	v_mul_f32_e32 v18, v67, v67
	v_fmac_f32_e32 v17, v64, v64
	v_fmac_f32_e32 v18, v66, v66
	v_add_f32_e32 v17, v17, v18
	v_add_f32_e32 v16, v17, v16
	v_mul_f32_e32 v17, v53, v53
	v_mul_f32_e32 v18, v55, v55
	v_fmac_f32_e32 v17, v52, v52
	v_fmac_f32_e32 v18, v54, v54
	v_add_f32_e32 v17, v17, v18
	v_add_f32_e32 v16, v17, v16
	v_mul_f32_e32 v17, v45, v45
	v_mul_f32_e32 v18, v47, v47
	v_fmac_f32_e32 v17, v44, v44
	v_fmac_f32_e32 v18, v46, v46
	v_add_f32_e32 v17, v17, v18
	v_add_f32_e32 v16, v17, v16
	v_mov_b32_e32 v17, v16
	v_mov_b32_e32 v18, v16
	s_nop 1
	v_permlane16_swap_b32_e32 v17, v18
	s_waitcnt lgkmcnt(0)
	v_add_f32_e32 v16, v17, v18
	v_mov_b32_e32 v17, v16
	v_mov_b32_e32 v18, v16
	s_nop 1
	v_permlane32_swap_b32_e32 v17, v18
	s_and_saveexec_b64 s[22:23], s[44:45]
	s_cbranch_execz .LBB0_1117
	s_lshl_b32 s5, s33, 10
	s_add_i32 s5, s59, s5
	s_waitcnt lgkmcnt(0)
	v_add_f32_e32 v16, v17, v18
	v_lshl_add_u32 v17, v221, 4, s5
	ds_write_b32 v17, v16 offset:2304
.LBB0_1117:
	s_or_b64 exec, exec, s[22:23]
	v_mul_f32_e32 v16, v57, v57
	s_waitcnt lgkmcnt(0)
	v_mul_f32_e32 v17, v59, v59
	v_fmac_f32_e32 v16, v56, v56
	v_fmac_f32_e32 v17, v58, v58
	v_add_f32_e32 v16, v16, v17
	v_mul_f32_e32 v17, v49, v49
	v_mul_f32_e32 v18, v51, v51
	v_fmac_f32_e32 v17, v48, v48
	v_fmac_f32_e32 v18, v50, v50
	v_add_f32_e32 v17, v17, v18
	v_add_f32_e32 v16, v17, v16
	v_mul_f32_e32 v17, v37, v37
	v_mul_f32_e32 v18, v39, v39
	v_fmac_f32_e32 v17, v36, v36
	v_fmac_f32_e32 v18, v38, v38
	v_add_f32_e32 v17, v17, v18
	v_add_f32_e32 v16, v17, v16
	v_mul_f32_e32 v17, v29, v29
	v_mul_f32_e32 v18, v31, v31
	v_fmac_f32_e32 v17, v28, v28
	v_fmac_f32_e32 v18, v30, v30
	v_add_f32_e32 v17, v17, v18
	v_add_f32_e32 v16, v17, v16
	v_mov_b32_e32 v17, v16
	v_mov_b32_e32 v18, v16
	s_nop 1
	v_permlane16_swap_b32_e32 v17, v18
	s_waitcnt lgkmcnt(0)
	v_add_f32_e32 v16, v17, v18
	v_mov_b32_e32 v17, v16
	v_mov_b32_e32 v18, v16
	s_nop 1
	v_permlane32_swap_b32_e32 v17, v18
	s_and_saveexec_b64 s[22:23], s[44:45]
	s_cbranch_execz .LBB0_1119
	s_lshl_b32 s5, s33, 10
	s_add_i32 s5, s59, s5
	s_waitcnt lgkmcnt(0)
	v_add_f32_e32 v16, v17, v18
	v_lshl_add_u32 v17, v221, 4, s5
	ds_write_b32 v17, v16 offset:2560
.LBB0_1119:
	s_or_b64 exec, exec, s[22:23]
	v_mul_f32_e32 v16, v41, v41
	s_waitcnt lgkmcnt(0)
	v_mul_f32_e32 v17, v43, v43
	v_fmac_f32_e32 v16, v40, v40
	v_fmac_f32_e32 v17, v42, v42
	v_add_f32_e32 v16, v16, v17
	v_mul_f32_e32 v17, v33, v33
	v_mul_f32_e32 v18, v35, v35
	v_fmac_f32_e32 v17, v32, v32
	v_fmac_f32_e32 v18, v34, v34
	v_add_f32_e32 v17, v17, v18
	v_add_f32_e32 v16, v17, v16
	v_mul_f32_e32 v17, v25, v25
	v_mul_f32_e32 v18, v27, v27
	v_fmac_f32_e32 v17, v24, v24
	v_fmac_f32_e32 v18, v26, v26
	v_add_f32_e32 v17, v17, v18
	v_add_f32_e32 v16, v17, v16
	v_mul_f32_e32 v17, v21, v21
	v_mul_f32_e32 v18, v23, v23
	v_fmac_f32_e32 v17, v20, v20
	v_fmac_f32_e32 v18, v22, v22
	v_add_f32_e32 v17, v17, v18
	v_add_f32_e32 v16, v17, v16
	v_mov_b32_e32 v17, v16
	v_mov_b32_e32 v18, v16
	s_nop 1
	v_permlane16_swap_b32_e32 v17, v18
	s_waitcnt lgkmcnt(0)
	v_add_f32_e32 v16, v17, v18
	v_mov_b32_e32 v17, v16
	v_mov_b32_e32 v18, v16
	s_nop 1
	v_permlane32_swap_b32_e32 v17, v18
	s_and_saveexec_b64 s[22:23], s[44:45]
	s_cbranch_execz .LBB0_1121
	s_lshl_b32 s5, s33, 10
	s_add_i32 s5, s59, s5
	s_waitcnt lgkmcnt(0)
	v_add_f32_e32 v16, v17, v18
	v_lshl_add_u32 v17, v221, 4, s5
	ds_write_b32 v17, v16 offset:2816
.LBB0_1121:
	s_or_b64 exec, exec, s[22:23]
	v_mul_f32_e32 v16, v13, v13
	s_waitcnt lgkmcnt(0)
	v_mul_f32_e32 v17, v15, v15
	v_fmac_f32_e32 v16, v12, v12
	v_fmac_f32_e32 v17, v14, v14
	v_add_f32_e32 v16, v16, v17
	v_mul_f32_e32 v17, v9, v9
	v_mul_f32_e32 v18, v11, v11
	v_fmac_f32_e32 v17, v8, v8
	v_fmac_f32_e32 v18, v10, v10
	v_add_f32_e32 v17, v17, v18
	v_add_f32_e32 v16, v16, v17
	v_mul_f32_e32 v17, v5, v5
	v_mul_f32_e32 v18, v7, v7
	v_fmac_f32_e32 v17, v4, v4
	v_fmac_f32_e32 v18, v6, v6
	v_add_f32_e32 v17, v17, v18
	v_add_f32_e32 v16, v17, v16
	v_mul_f32_e32 v17, v1, v1
	v_mul_f32_e32 v18, v3, v3
	v_fmac_f32_e32 v17, v0, v0
	v_fmac_f32_e32 v18, v2, v2
	v_add_f32_e32 v17, v17, v18
	v_add_f32_e32 v16, v17, v16
	s_lshl_b32 s60, s33, 4
	v_mov_b32_e32 v17, v16
	v_mov_b32_e32 v18, v16
	s_nop 1
	v_permlane16_swap_b32_e32 v17, v18
	s_waitcnt lgkmcnt(0)
	v_add_f32_e32 v16, v17, v18
	v_mov_b32_e32 v17, v16
	v_mov_b32_e32 v19, v16
	s_nop 1
	v_permlane32_swap_b32_e32 v17, v19
	s_and_saveexec_b64 s[22:23], s[44:45]
	s_cbranch_execz .LBB0_1123
	s_add_i32 s5, s60, 0x100
	v_or_b32_e32 v18, s5, v221
	v_lshl_add_u32 v18, v18, 4, s59
	s_waitcnt lgkmcnt(0)
	v_add_f32_e32 v16, v17, v19
	ds_write_b32 v18, v16

.LBB0_1144:
	s_or_b64 exec, exec, s[28:29]
	v_readlane_b32 s24, v254, 52
	v_readlane_b32 s25, v254, 53
	s_waitcnt lgkmcnt(0)
	s_mov_b32 s30, s24
	s_mul_i32 s25, s30, 0x1b000
	s_mul_hi_u32 s24, s24, 0x1b000
	s_add_u32 s28, s56, s25
	s_addc_u32 s29, s57, s24
	s_add_u32 s36, s28, 0x100000
	s_addc_u32 s37, s29, 0
	s_lshl_b32 s96, s30, 10
	s_lshl_b64 s[24:25], s[96:97], 2
	s_add_u32 s30, s52, s24
	s_addc_u32 s31, s53, s25
	s_ashr_i32 s38, s4, 3
	s_mul_i32 s34, s38, 0x3000
	s_mul_hi_i32 s35, s38, 0x3000
	s_add_u32 s34, s36, s34
	s_addc_u32 s35, s37, s35
	v_lshlrev_b64 v[158:159], 2, v[156:157]
	v_lshl_add_u64 v[16:17], s[34:35], 0, v[158:159]
	s_mov_b64 s[34:35], 0x2000
	v_lshl_add_u64 v[204:205], s[30:31], 0, v[158:159]
	s_movk_i32 s30, 0x2000
	v_lshl_add_u64 v[174:175], v[16:17], 0, s[34:35]
	v_add_co_u32_e32 v16, vcc, s30, v16
	s_waitcnt lgkmcnt(0)
	s_barrier
	s_nop 0
	v_addc_co_u32_e32 v17, vcc, 0, v17, vcc
	global_load_dwordx4 v[166:169], v[16:17], off
	s_nop 0
	global_load_dwordx4 v[16:19], v[204:205], off
	v_lshl_or_b32 v154, s33, 6, v221
	v_lshlrev_b32_e32 v148, 3, v165
	v_and_b32_e32 v161, 8, v148
	v_lshl_add_u32 v220, v154, 2, 0
	v_lshlrev_b32_e32 v154, 9, v154
	v_add3_u32 v161, 0, v161, v154
	v_bitop3_b32 v154, v164, v221, s63 bitop3:0x36
	v_or_b32_e32 v155, s63, v164
	v_bitop3_b32 v165, v155, v221, 18 bitop3:0x36
	s_add_u32 s28, s28, 0x11a000
	s_addc_u32 s29, s29, 0
	s_lshl_b32 s30, s60, 2
	v_or_b32_e32 v208, 0x90, v156
	s_add_i32 s30, s30, 0
	v_ashrrev_i32_e32 v209, 31, v208
	v_lshl_add_u32 v219, v221, 2, s30
	s_waitcnt vmcnt(0)
	v_pk_mul_f32 v[176:177], v[168:169], v[18:19]
	v_pk_mul_f32 v[178:179], v[166:167], v[16:17]
	global_load_dwordx4 v[166:169], v[174:175], off offset:64
	global_load_dwordx4 v[170:173], v[204:205], off offset:64
	s_waitcnt vmcnt(0)
	v_pk_mul_f32 v[180:181], v[168:169], v[172:173]
	v_pk_mul_f32 v[182:183], v[166:167], v[170:171]
	global_load_dwordx4 v[166:169], v[174:175], off offset:512
	global_load_dwordx4 v[170:173], v[204:205], off offset:512
	s_waitcnt vmcnt(0)
	v_pk_mul_f32 v[184:185], v[168:169], v[172:173]
	v_pk_mul_f32 v[186:187], v[166:167], v[170:171]
	global_load_dwordx4 v[166:169], v[174:175], off offset:576
	global_load_dwordx4 v[170:173], v[204:205], off offset:576
	ds_read_b32 v148, v220 offset:8192
	v_lshlrev_b32_e32 v175, 4, v165
	v_add_u32_e32 v226, v161, v175
	v_or_b32_e32 v174, 16, v221
	v_bitop3_b32 v164, v164, v174, s63 bitop3:0x36
	v_lshlrev_b32_e32 v200, 4, v164
	s_waitcnt vmcnt(0)
	v_pk_mul_f32 v[188:189], v[168:169], v[172:173]
	v_lshlrev_b32_e32 v168, 4, v154
	v_add_u32_e32 v223, v161, v168
	v_pk_mul_f32 v[190:191], v[166:167], v[170:171]
	ds_read_b64 v[166:167], v223 offset:10240
	s_waitcnt lgkmcnt(1)
	v_pk_mul_f32 v[172:173], v[144:145], v[148:149] op_sel_hi:[1,0]
	v_pk_mul_f32 v[144:145], v[146:147], v[148:149] op_sel_hi:[1,0]
	v_bitop3_b32 v154, v155, v221, 2 bitop3:0x36
	v_lshlrev_b32_e32 v169, 4, v154
	s_waitcnt lgkmcnt(0)
	v_lshlrev_b32_e32 v170, 16, v166
	v_and_b32_e32 v171, 0xffff0000, v166
	v_lshlrev_b32_e32 v166, 16, v167
	v_and_b32_e32 v167, 0xffff0000, v167
	v_pk_fma_f32 v[144:145], v[176:177], v[144:145], v[166:167]
	v_pk_fma_f32 v[146:147], v[178:179], v[172:173], v[170:171]
	v_cvt_pk_bf16_f32 v167, v144, v145
	v_cvt_pk_bf16_f32 v166, v146, v147
	v_add_u32_e32 v224, v161, v169
	ds_write_b64 v223, v[166:167] offset:10240
	ds_read_b64 v[166:167], v224 offset:10240
	v_pk_mul_f32 v[172:173], v[140:141], v[148:149] op_sel_hi:[1,0]
	v_pk_mul_f32 v[140:141], v[142:143], v[148:149] op_sel_hi:[1,0]
	v_bitop3_b32 v154, v155, v221, 16 bitop3:0x36
	v_lshlrev_b32_e32 v154, 4, v154
	s_waitcnt lgkmcnt(0)
	v_lshlrev_b32_e32 v170, 16, v166
	v_and_b32_e32 v171, 0xffff0000, v166
	v_lshlrev_b32_e32 v166, 16, v167
	v_and_b32_e32 v167, 0xffff0000, v167
	v_pk_fma_f32 v[140:141], v[180:181], v[140:141], v[166:167]
	v_pk_fma_f32 v[142:143], v[182:183], v[172:173], v[170:171]
	v_cvt_pk_bf16_f32 v167, v140, v141
	v_cvt_pk_bf16_f32 v166, v142, v143
	v_add_u32_e32 v225, v161, v154
	ds_write_b64 v224, v[166:167] offset:10240
	ds_read_b64 v[166:167], v225 offset:10240
	v_pk_mul_f32 v[172:173], v[136:137], v[148:149] op_sel_hi:[1,0]
	v_pk_mul_f32 v[136:137], v[138:139], v[148:149] op_sel_hi:[1,0]
	s_waitcnt lgkmcnt(0)
	v_lshlrev_b32_e32 v170, 16, v166
	v_and_b32_e32 v171, 0xffff0000, v166
	v_lshlrev_b32_e32 v166, 16, v167
	v_and_b32_e32 v167, 0xffff0000, v167
	v_pk_fma_f32 v[136:137], v[184:185], v[136:137], v[166:167]
	v_pk_fma_f32 v[138:139], v[186:187], v[172:173], v[170:171]
	v_cvt_pk_bf16_f32 v167, v136, v137
	v_cvt_pk_bf16_f32 v166, v138, v139
	ds_write_b64 v225, v[166:167] offset:10240
	ds_read_b64 v[166:167], v226 offset:10240
	v_pk_mul_f32 v[172:173], v[124:125], v[148:149] op_sel_hi:[1,0]
	v_pk_mul_f32 v[124:125], v[126:127], v[148:149] op_sel_hi:[1,0]
	s_waitcnt lgkmcnt(0)
	v_lshlrev_b32_e32 v170, 16, v166
	v_and_b32_e32 v171, 0xffff0000, v166
	v_lshlrev_b32_e32 v166, 16, v167
	v_and_b32_e32 v167, 0xffff0000, v167
	v_pk_fma_f32 v[124:125], v[188:189], v[124:125], v[166:167]
	v_pk_fma_f32 v[126:127], v[190:191], v[172:173], v[170:171]
	v_cvt_pk_bf16_f32 v167, v124, v125
	v_cvt_pk_bf16_f32 v166, v126, v127
	v_add_u32_e32 v172, 0x2000, v161
	ds_write_b64 v226, v[166:167] offset:10240
	v_add_u32_e32 v227, v172, v200
	ds_read_b32 v148, v220 offset:8256
	ds_read_b64 v[164:165], v227 offset:10240
	s_waitcnt lgkmcnt(1)
	v_pk_mul_f32 v[170:171], v[132:133], v[148:149] op_sel_hi:[1,0]
	s_waitcnt lgkmcnt(0)
	v_lshlrev_b32_e32 v166, 16, v164
	v_and_b32_e32 v167, 0xffff0000, v164
	v_lshlrev_b32_e32 v164, 16, v165
	v_and_b32_e32 v165, 0xffff0000, v165
	v_pk_mul_f32 v[132:133], v[134:135], v[148:149] op_sel_hi:[1,0]
	v_pk_fma_f32 v[134:135], v[178:179], v[170:171], v[166:167]
	v_pk_fma_f32 v[132:133], v[176:177], v[132:133], v[164:165]
	v_cvt_pk_bf16_f32 v164, v134, v135
	v_cvt_pk_bf16_f32 v165, v132, v133
	ds_write_b64 v227, v[164:165] offset:10240
	v_bitop3_b32 v164, v155, v174, 2 bitop3:0x36
	v_lshlrev_b32_e32 v201, 4, v164
	v_add_u32_e32 v228, v172, v201
	ds_read_b64 v[164:165], v228 offset:10240
	v_pk_mul_f32 v[170:171], v[128:129], v[148:149] op_sel_hi:[1,0]
	v_pk_mul_f32 v[128:129], v[130:131], v[148:149] op_sel_hi:[1,0]
	s_waitcnt lgkmcnt(0)
	v_lshlrev_b32_e32 v166, 16, v164
	v_and_b32_e32 v167, 0xffff0000, v164
	v_lshlrev_b32_e32 v164, 16, v165
	v_and_b32_e32 v165, 0xffff0000, v165
	v_pk_fma_f32 v[128:129], v[180:181], v[128:129], v[164:165]
	v_pk_fma_f32 v[130:131], v[182:183], v[170:171], v[166:167]
	v_cvt_pk_bf16_f32 v165, v128, v129
	v_cvt_pk_bf16_f32 v164, v130, v131
	ds_write_b64 v228, v[164:165] offset:10240
	v_bitop3_b32 v164, v155, v221, 16 bitop3:0x14
	v_lshlrev_b32_e32 v206, 4, v164
	v_add_u32_e32 v229, v172, v206
	ds_read_b64 v[164:165], v229 offset:10240
	v_pk_mul_f32 v[170:171], v[116:117], v[148:149] op_sel_hi:[1,0]
	v_pk_mul_f32 v[116:117], v[118:119], v[148:149] op_sel_hi:[1,0]
	v_bitop3_b32 v155, v155, v174, 18 bitop3:0x36
	v_lshlrev_b32_e32 v155, 4, v155
	s_waitcnt lgkmcnt(0)
	v_lshlrev_b32_e32 v166, 16, v164
	v_and_b32_e32 v167, 0xffff0000, v164
	v_lshlrev_b32_e32 v164, 16, v165
	v_and_b32_e32 v165, 0xffff0000, v165
	v_pk_fma_f32 v[116:117], v[184:185], v[116:117], v[164:165]
	v_pk_fma_f32 v[118:119], v[186:187], v[170:171], v[166:167]
	v_cvt_pk_bf16_f32 v165, v116, v117
	v_cvt_pk_bf16_f32 v164, v118, v119
	v_add_u32_e32 v230, v172, v155
	ds_write_b64 v229, v[164:165] offset:10240
	ds_read_b64 v[164:165], v230 offset:10240
	v_pk_mul_f32 v[170:171], v[108:109], v[148:149] op_sel_hi:[1,0]
	v_pk_mul_f32 v[108:109], v[110:111], v[148:149] op_sel_hi:[1,0]
	v_add_u32_e32 v172, 0x4000, v161
	v_add_u32_e32 v231, v172, v168
	s_waitcnt lgkmcnt(0)
	v_lshlrev_b32_e32 v166, 16, v164
	v_and_b32_e32 v167, 0xffff0000, v164
	v_lshlrev_b32_e32 v164, 16, v165
	v_and_b32_e32 v165, 0xffff0000, v165
	v_pk_fma_f32 v[108:109], v[188:189], v[108:109], v[164:165]
	v_pk_fma_f32 v[110:111], v[190:191], v[170:171], v[166:167]
	v_cvt_pk_bf16_f32 v165, v108, v109
	v_cvt_pk_bf16_f32 v164, v110, v111
	ds_write_b64 v230, v[164:165] offset:10240
	ds_read_b32 v148, v220 offset:8320
	ds_read_b64 v[164:165], v231 offset:10240
	v_add_u32_e32 v232, v172, v169
	v_add_u32_e32 v233, v172, v154
	v_add_u32_e32 v234, v172, v175
	s_waitcnt lgkmcnt(1)
	v_pk_mul_f32 v[170:171], v[120:121], v[148:149] op_sel_hi:[1,0]
	s_waitcnt lgkmcnt(0)
	v_lshlrev_b32_e32 v166, 16, v164
	v_and_b32_e32 v167, 0xffff0000, v164
	v_lshlrev_b32_e32 v164, 16, v165
	v_and_b32_e32 v165, 0xffff0000, v165
	v_pk_mul_f32 v[120:121], v[122:123], v[148:149] op_sel_hi:[1,0]
	v_pk_fma_f32 v[122:123], v[178:179], v[170:171], v[166:167]
	v_pk_fma_f32 v[120:121], v[176:177], v[120:121], v[164:165]
	v_cvt_pk_bf16_f32 v164, v122, v123
	v_cvt_pk_bf16_f32 v165, v120, v121
	ds_write_b64 v231, v[164:165] offset:10240
	ds_read_b64 v[164:165], v232 offset:10240
	v_pk_mul_f32 v[170:171], v[112:113], v[148:149] op_sel_hi:[1,0]
	v_pk_mul_f32 v[112:113], v[114:115], v[148:149] op_sel_hi:[1,0]
	v_add_u32_e32 v172, 0x6000, v161
	v_add_u32_e32 v235, v172, v200
	s_waitcnt lgkmcnt(0)
	v_lshlrev_b32_e32 v166, 16, v164
	v_and_b32_e32 v167, 0xffff0000, v164
	v_lshlrev_b32_e32 v164, 16, v165
	v_and_b32_e32 v165, 0xffff0000, v165
	v_pk_fma_f32 v[112:113], v[180:181], v[112:113], v[164:165]
	v_pk_fma_f32 v[114:115], v[182:183], v[170:171], v[166:167]
	v_cvt_pk_bf16_f32 v165, v112, v113
	v_cvt_pk_bf16_f32 v164, v114, v115
	ds_write_b64 v232, v[164:165] offset:10240
	ds_read_b64 v[164:165], v233 offset:10240
	v_pk_mul_f32 v[170:171], v[100:101], v[148:149] op_sel_hi:[1,0]
	v_pk_mul_f32 v[100:101], v[102:103], v[148:149] op_sel_hi:[1,0]
	v_add_u32_e32 v236, v172, v201
	v_add_u32_e32 v237, v172, v206
	s_waitcnt lgkmcnt(0)
	v_lshlrev_b32_e32 v166, 16, v164
	v_and_b32_e32 v167, 0xffff0000, v164
	v_lshlrev_b32_e32 v164, 16, v165
	v_and_b32_e32 v165, 0xffff0000, v165
	v_pk_fma_f32 v[100:101], v[184:185], v[100:101], v[164:165]
	v_pk_fma_f32 v[102:103], v[186:187], v[170:171], v[166:167]
	v_cvt_pk_bf16_f32 v165, v100, v101
	v_cvt_pk_bf16_f32 v164, v102, v103
	ds_write_b64 v233, v[164:165] offset:10240
	ds_read_b64 v[164:165], v234 offset:10240
	v_pk_mul_f32 v[170:171], v[92:93], v[148:149] op_sel_hi:[1,0]
	v_pk_mul_f32 v[92:93], v[94:95], v[148:149] op_sel_hi:[1,0]
	v_add_u32_e32 v238, v172, v155
	v_add_u32_e32 v172, 0x10000, v161
	s_waitcnt lgkmcnt(0)
	v_lshlrev_b32_e32 v166, 16, v164
	v_and_b32_e32 v167, 0xffff0000, v164
	v_lshlrev_b32_e32 v164, 16, v165
	v_and_b32_e32 v165, 0xffff0000, v165
	v_pk_fma_f32 v[92:93], v[188:189], v[92:93], v[164:165]
	v_pk_fma_f32 v[94:95], v[190:191], v[170:171], v[166:167]
	v_cvt_pk_bf16_f32 v165, v92, v93
	v_cvt_pk_bf16_f32 v164, v94, v95
	ds_write_b64 v234, v[164:165] offset:10240
	ds_read_b32 v148, v220 offset:8384
	ds_read_b64 v[164:165], v235 offset:10240
	v_add_u32_e32 v239, v172, v168
	v_add_u32_e32 v240, v172, v169
	v_add_u32_e32 v241, v172, v154
	s_waitcnt lgkmcnt(1)
	v_pk_mul_f32 v[170:171], v[104:105], v[148:149] op_sel_hi:[1,0]
	s_waitcnt lgkmcnt(0)
	v_lshlrev_b32_e32 v166, 16, v164
	v_and_b32_e32 v167, 0xffff0000, v164
	v_lshlrev_b32_e32 v164, 16, v165
	v_and_b32_e32 v165, 0xffff0000, v165
	v_pk_mul_f32 v[104:105], v[106:107], v[148:149] op_sel_hi:[1,0]
	v_pk_fma_f32 v[106:107], v[178:179], v[170:171], v[166:167]
	v_pk_fma_f32 v[104:105], v[176:177], v[104:105], v[164:165]
	v_cvt_pk_bf16_f32 v164, v106, v107
	v_cvt_pk_bf16_f32 v165, v104, v105
	ds_write_b64 v235, v[164:165] offset:10240
	ds_read_b64 v[164:165], v236 offset:10240
	v_pk_mul_f32 v[170:171], v[96:97], v[148:149] op_sel_hi:[1,0]
	v_pk_mul_f32 v[96:97], v[98:99], v[148:149] op_sel_hi:[1,0]
	v_add_u32_e32 v242, v172, v175
	v_add_u32_e32 v172, 0x12000, v161
	s_waitcnt lgkmcnt(0)
	v_lshlrev_b32_e32 v166, 16, v164
	v_and_b32_e32 v167, 0xffff0000, v164
	v_lshlrev_b32_e32 v164, 16, v165
	v_and_b32_e32 v165, 0xffff0000, v165
	v_pk_fma_f32 v[96:97], v[180:181], v[96:97], v[164:165]
	v_pk_fma_f32 v[98:99], v[182:183], v[170:171], v[166:167]
	v_cvt_pk_bf16_f32 v165, v96, v97
	v_cvt_pk_bf16_f32 v164, v98, v99
	ds_write_b64 v236, v[164:165] offset:10240
	ds_read_b64 v[164:165], v237 offset:10240
	v_pk_mul_f32 v[170:171], v[88:89], v[148:149] op_sel_hi:[1,0]
	v_pk_mul_f32 v[88:89], v[90:91], v[148:149] op_sel_hi:[1,0]
	v_add_u32_e32 v243, v172, v200
	v_add_u32_e32 v244, v172, v201
	s_waitcnt lgkmcnt(0)
	v_lshlrev_b32_e32 v166, 16, v164
	v_and_b32_e32 v167, 0xffff0000, v164
	v_lshlrev_b32_e32 v164, 16, v165
	v_and_b32_e32 v165, 0xffff0000, v165
	v_pk_fma_f32 v[88:89], v[184:185], v[88:89], v[164:165]
	v_pk_fma_f32 v[90:91], v[186:187], v[170:171], v[166:167]
	v_cvt_pk_bf16_f32 v165, v88, v89
	v_cvt_pk_bf16_f32 v164, v90, v91
	ds_write_b64 v237, v[164:165] offset:10240
	ds_read_b64 v[164:165], v238 offset:10240
	v_pk_mul_f32 v[170:171], v[84:85], v[148:149] op_sel_hi:[1,0]
	v_pk_mul_f32 v[84:85], v[86:87], v[148:149] op_sel_hi:[1,0]
	v_add_u32_e32 v245, v172, v206
	v_add_u32_e32 v246, v172, v155
	s_waitcnt lgkmcnt(0)
	v_lshlrev_b32_e32 v166, 16, v164
	v_and_b32_e32 v167, 0xffff0000, v164
	v_lshlrev_b32_e32 v164, 16, v165
	v_and_b32_e32 v165, 0xffff0000, v165
	v_pk_fma_f32 v[84:85], v[188:189], v[84:85], v[164:165]
	v_pk_fma_f32 v[86:87], v[190:191], v[170:171], v[166:167]
	v_cvt_pk_bf16_f32 v165, v84, v85
	v_cvt_pk_bf16_f32 v164, v86, v87
	ds_write_b64 v238, v[164:165] offset:10240
	ds_read_b32 v148, v220 offset:8704
	ds_read_b64 v[164:165], v239 offset:10240
	s_waitcnt lgkmcnt(1)
	v_pk_mul_f32 v[170:171], v[80:81], v[148:149] op_sel_hi:[1,0]
	s_waitcnt lgkmcnt(0)
	v_lshlrev_b32_e32 v166, 16, v164
	v_and_b32_e32 v167, 0xffff0000, v164
	v_lshlrev_b32_e32 v164, 16, v165
	v_and_b32_e32 v165, 0xffff0000, v165
	v_pk_mul_f32 v[80:81], v[82:83], v[148:149] op_sel_hi:[1,0]
	v_pk_fma_f32 v[82:83], v[178:179], v[170:171], v[166:167]
	v_pk_fma_f32 v[80:81], v[176:177], v[80:81], v[164:165]
	v_cvt_pk_bf16_f32 v164, v82, v83
	v_cvt_pk_bf16_f32 v165, v80, v81
	ds_write_b64 v239, v[164:165] offset:10240
	ds_read_b64 v[164:165], v240 offset:10240
	v_pk_mul_f32 v[170:171], v[76:77], v[148:149] op_sel_hi:[1,0]
	v_pk_mul_f32 v[76:77], v[78:79], v[148:149] op_sel_hi:[1,0]
	s_waitcnt lgkmcnt(0)
	v_lshlrev_b32_e32 v166, 16, v164
	v_and_b32_e32 v167, 0xffff0000, v164
	v_lshlrev_b32_e32 v164, 16, v165
	v_and_b32_e32 v165, 0xffff0000, v165
	v_pk_fma_f32 v[76:77], v[180:181], v[76:77], v[164:165]
	v_pk_fma_f32 v[78:79], v[182:183], v[170:171], v[166:167]
	v_cvt_pk_bf16_f32 v165, v76, v77
	v_cvt_pk_bf16_f32 v164, v78, v79
	ds_write_b64 v240, v[164:165] offset:10240
	ds_read_b64 v[164:165], v241 offset:10240
	v_pk_mul_f32 v[170:171], v[68:69], v[148:149] op_sel_hi:[1,0]
	v_pk_mul_f32 v[68:69], v[70:71], v[148:149] op_sel_hi:[1,0]
	s_waitcnt lgkmcnt(0)
	v_lshlrev_b32_e32 v166, 16, v164
	v_and_b32_e32 v167, 0xffff0000, v164
	v_lshlrev_b32_e32 v164, 16, v165
	v_and_b32_e32 v165, 0xffff0000, v165
	v_pk_fma_f32 v[68:69], v[184:185], v[68:69], v[164:165]
	v_pk_fma_f32 v[70:71], v[186:187], v[170:171], v[166:167]
	v_cvt_pk_bf16_f32 v165, v68, v69
	v_cvt_pk_bf16_f32 v164, v70, v71
	ds_write_b64 v241, v[164:165] offset:10240
	ds_read_b64 v[164:165], v242 offset:10240
	v_pk_mul_f32 v[170:171], v[60:61], v[148:149] op_sel_hi:[1,0]
	v_pk_mul_f32 v[60:61], v[62:63], v[148:149] op_sel_hi:[1,0]
	s_waitcnt lgkmcnt(0)
	v_lshlrev_b32_e32 v166, 16, v164
	v_and_b32_e32 v167, 0xffff0000, v164
	v_lshlrev_b32_e32 v164, 16, v165
	v_and_b32_e32 v165, 0xffff0000, v165
	v_pk_fma_f32 v[60:61], v[188:189], v[60:61], v[164:165]
	v_pk_fma_f32 v[62:63], v[190:191], v[170:171], v[166:167]
	v_cvt_pk_bf16_f32 v165, v60, v61
	v_cvt_pk_bf16_f32 v164, v62, v63
	ds_write_b64 v242, v[164:165] offset:10240
	ds_read_b32 v148, v220 offset:8768
	ds_read_b64 v[164:165], v243 offset:10240
	s_waitcnt lgkmcnt(1)
	v_pk_mul_f32 v[170:171], v[72:73], v[148:149] op_sel_hi:[1,0]
	s_waitcnt lgkmcnt(0)
	v_lshlrev_b32_e32 v166, 16, v164
	v_and_b32_e32 v167, 0xffff0000, v164
	v_lshlrev_b32_e32 v164, 16, v165
	v_and_b32_e32 v165, 0xffff0000, v165
	v_pk_mul_f32 v[72:73], v[74:75], v[148:149] op_sel_hi:[1,0]
	v_pk_fma_f32 v[74:75], v[178:179], v[170:171], v[166:167]
	v_pk_fma_f32 v[72:73], v[176:177], v[72:73], v[164:165]
	v_cvt_pk_bf16_f32 v164, v74, v75
	v_cvt_pk_bf16_f32 v165, v72, v73
	ds_write_b64 v243, v[164:165] offset:10240
	ds_read_b64 v[164:165], v244 offset:10240
	v_pk_mul_f32 v[170:171], v[64:65], v[148:149] op_sel_hi:[1,0]
	v_pk_mul_f32 v[64:65], v[66:67], v[148:149] op_sel_hi:[1,0]
	v_pk_mul_f32 v[44:45], v[44:45], v[148:149] op_sel_hi:[1,0]
	v_pk_mul_f32 v[46:47], v[46:47], v[148:149] op_sel_hi:[1,0]
	s_waitcnt lgkmcnt(0)
	v_lshlrev_b32_e32 v166, 16, v164
	v_and_b32_e32 v167, 0xffff0000, v164
	v_lshlrev_b32_e32 v164, 16, v165
	v_and_b32_e32 v165, 0xffff0000, v165
	v_pk_fma_f32 v[64:65], v[180:181], v[64:65], v[164:165]
	v_pk_fma_f32 v[66:67], v[182:183], v[170:171], v[166:167]
	v_cvt_pk_bf16_f32 v165, v64, v65
	v_cvt_pk_bf16_f32 v164, v66, v67
	ds_write_b64 v244, v[164:165] offset:10240
	ds_read_b64 v[164:165], v245 offset:10240
	v_pk_mul_f32 v[170:171], v[52:53], v[148:149] op_sel_hi:[1,0]
	v_pk_mul_f32 v[52:53], v[54:55], v[148:149] op_sel_hi:[1,0]
	s_waitcnt lgkmcnt(0)
	v_lshlrev_b32_e32 v166, 16, v164
	v_and_b32_e32 v167, 0xffff0000, v164
	v_lshlrev_b32_e32 v164, 16, v165
	v_and_b32_e32 v165, 0xffff0000, v165
	v_pk_fma_f32 v[52:53], v[184:185], v[52:53], v[164:165]
	v_pk_fma_f32 v[54:55], v[186:187], v[170:171], v[166:167]
	v_cvt_pk_bf16_f32 v165, v52, v53
	v_cvt_pk_bf16_f32 v164, v54, v55
	ds_write_b64 v245, v[164:165] offset:10240
	ds_read_b64 v[164:165], v246 offset:10240
	s_waitcnt lgkmcnt(0)
	v_lshlrev_b32_e32 v166, 16, v164
	v_and_b32_e32 v167, 0xffff0000, v164
	v_lshlrev_b32_e32 v164, 16, v165
	v_and_b32_e32 v165, 0xffff0000, v165
	v_pk_fma_f32 v[164:165], v[188:189], v[46:47], v[164:165]
	v_pk_fma_f32 v[166:167], v[190:191], v[44:45], v[166:167]
	v_cvt_pk_bf16_f32 v45, v164, v165
	v_cvt_pk_bf16_f32 v44, v166, v167
	ds_write_b64 v246, v[44:45] offset:10240
	v_add_u32_e32 v45, 0x14000, v161
	v_add_u32_e32 v247, v45, v168
	ds_read_b32 v44, v220 offset:8832
	ds_read_b64 v[46:47], v247 offset:10240
	v_add_u32_e32 v248, v45, v169
	v_add_u32_e32 v249, v45, v154
	v_add_u32_e32 v250, v45, v175
	s_waitcnt lgkmcnt(1)
	v_pk_mul_f32 v[172:173], v[56:57], v[44:45] op_sel_hi:[1,0]
	s_waitcnt lgkmcnt(0)
	v_lshlrev_b32_e32 v170, 16, v46
	v_and_b32_e32 v171, 0xffff0000, v46
	v_lshlrev_b32_e32 v46, 16, v47
	v_and_b32_e32 v47, 0xffff0000, v47
	v_pk_mul_f32 v[56:57], v[58:59], v[44:45] op_sel_hi:[1,0]
	v_pk_fma_f32 v[58:59], v[178:179], v[172:173], v[170:171]
	v_pk_fma_f32 v[56:57], v[176:177], v[56:57], v[46:47]
	v_cvt_pk_bf16_f32 v46, v58, v59
	v_cvt_pk_bf16_f32 v47, v56, v57
	ds_write_b64 v247, v[46:47] offset:10240
	ds_read_b64 v[46:47], v248 offset:10240
	v_pk_mul_f32 v[170:171], v[48:49], v[44:45] op_sel_hi:[1,0]
	v_pk_mul_f32 v[48:49], v[50:51], v[44:45] op_sel_hi:[1,0]
	v_pk_mul_f32 v[36:37], v[36:37], v[44:45] op_sel_hi:[1,0]
	v_pk_mul_f32 v[38:39], v[38:39], v[44:45] op_sel_hi:[1,0]
	s_waitcnt lgkmcnt(0)
	v_lshlrev_b32_e32 v168, 16, v46
	v_and_b32_e32 v169, 0xffff0000, v46
	v_lshlrev_b32_e32 v46, 16, v47
	v_and_b32_e32 v47, 0xffff0000, v47
	v_pk_fma_f32 v[48:49], v[180:181], v[48:49], v[46:47]
	v_pk_fma_f32 v[50:51], v[182:183], v[170:171], v[168:169]
	v_cvt_pk_bf16_f32 v47, v48, v49
	v_cvt_pk_bf16_f32 v46, v50, v51
	ds_write_b64 v248, v[46:47] offset:10240
	ds_read_b64 v[46:47], v249 offset:10240
	v_pk_mul_f32 v[28:29], v[28:29], v[44:45] op_sel_hi:[1,0]
	v_pk_mul_f32 v[30:31], v[30:31], v[44:45] op_sel_hi:[1,0]
	v_mul_f32_e32 v154, v147, v147
	v_fmac_f32_e32 v154, v146, v146
	s_waitcnt lgkmcnt(0)
	v_lshlrev_b32_e32 v170, 16, v46
	v_and_b32_e32 v171, 0xffff0000, v46
	v_lshlrev_b32_e32 v46, 16, v47
	v_and_b32_e32 v47, 0xffff0000, v47
	v_pk_fma_f32 v[168:169], v[184:185], v[38:39], v[46:47]
	v_pk_fma_f32 v[170:171], v[186:187], v[36:37], v[170:171]
	v_cvt_pk_bf16_f32 v37, v168, v169
	v_cvt_pk_bf16_f32 v36, v170, v171
	ds_write_b64 v249, v[36:37] offset:10240
	ds_read_b64 v[36:37], v250 offset:10240
	s_waitcnt lgkmcnt(0)
	v_lshlrev_b32_e32 v38, 16, v36
	v_and_b32_e32 v39, 0xffff0000, v36
	v_lshlrev_b32_e32 v36, 16, v37
	v_and_b32_e32 v37, 0xffff0000, v37
	v_pk_fma_f32 v[172:173], v[188:189], v[30:31], v[36:37]
	v_pk_fma_f32 v[174:175], v[190:191], v[28:29], v[38:39]
	v_cvt_pk_bf16_f32 v29, v172, v173
	v_cvt_pk_bf16_f32 v28, v174, v175
	ds_write_b64 v250, v[28:29] offset:10240
	v_add_u32_e32 v29, 0x16000, v161
	v_add_u32_e32 v251, v29, v200
	ds_read_b32 v28, v220 offset:8896
	ds_read_b64 v[30:31], v251 offset:10240
	v_add_u32_e32 v211, v29, v201
	v_add_u32_e32 v212, v29, v206
	v_add_u32_e32 v213, v29, v155
	s_waitcnt lgkmcnt(1)
	v_pk_mul_f32 v[38:39], v[40:41], v[28:29] op_sel_hi:[1,0]
	s_waitcnt lgkmcnt(0)
	v_lshlrev_b32_e32 v36, 16, v30
	v_and_b32_e32 v37, 0xffff0000, v30
	v_lshlrev_b32_e32 v30, 16, v31
	v_and_b32_e32 v31, 0xffff0000, v31
	v_pk_mul_f32 v[40:41], v[42:43], v[28:29] op_sel_hi:[1,0]
	v_pk_fma_f32 v[178:179], v[178:179], v[38:39], v[36:37]
	v_pk_fma_f32 v[176:177], v[176:177], v[40:41], v[30:31]
	v_cvt_pk_bf16_f32 v30, v178, v179
	v_cvt_pk_bf16_f32 v31, v176, v177
	ds_write_b64 v251, v[30:31] offset:10240
	ds_read_b64 v[30:31], v211 offset:10240
	v_pk_mul_f32 v[32:33], v[32:33], v[28:29] op_sel_hi:[1,0]
	v_pk_mul_f32 v[34:35], v[34:35], v[28:29] op_sel_hi:[1,0]
	v_pk_mul_f32 v[24:25], v[24:25], v[28:29] op_sel_hi:[1,0]
	v_pk_mul_f32 v[26:27], v[26:27], v[28:29] op_sel_hi:[1,0]
	s_waitcnt lgkmcnt(0)
	v_lshlrev_b32_e32 v36, 16, v30
	v_and_b32_e32 v37, 0xffff0000, v30
	v_lshlrev_b32_e32 v30, 16, v31
	v_and_b32_e32 v31, 0xffff0000, v31
	v_pk_fma_f32 v[180:181], v[180:181], v[34:35], v[30:31]
	v_pk_fma_f32 v[182:183], v[182:183], v[32:33], v[36:37]
	v_cvt_pk_bf16_f32 v31, v180, v181
	v_cvt_pk_bf16_f32 v30, v182, v183
	ds_write_b64 v211, v[30:31] offset:10240
	ds_read_b64 v[30:31], v212 offset:10240
	v_pk_mul_f32 v[20:21], v[20:21], v[28:29] op_sel_hi:[1,0]
	v_pk_mul_f32 v[22:23], v[22:23], v[28:29] op_sel_hi:[1,0]
	v_or_b32_e32 v200, 16, v156
	v_or_b32_e32 v206, 0x80, v156
	s_waitcnt lgkmcnt(0)
	v_lshlrev_b32_e32 v32, 16, v30
	v_and_b32_e32 v33, 0xffff0000, v30
	v_lshlrev_b32_e32 v30, 16, v31
	v_and_b32_e32 v31, 0xffff0000, v31
	v_pk_fma_f32 v[184:185], v[184:185], v[26:27], v[30:31]
	v_pk_fma_f32 v[186:187], v[186:187], v[24:25], v[32:33]
	v_cvt_pk_bf16_f32 v25, v184, v185
	v_cvt_pk_bf16_f32 v24, v186, v187
	ds_write_b64 v212, v[24:25] offset:10240
	ds_read_b64 v[24:25], v213 offset:10240
	v_ashrrev_i32_e32 v201, 31, v200
	v_ashrrev_i32_e32 v207, 31, v206
	v_lshl_add_u64 v[28:29], v[206:207], 2, s[28:29]
	v_lshl_add_u64 v[40:41], v[208:209], 2, s[28:29]
	s_waitcnt lgkmcnt(0)
	v_lshlrev_b32_e32 v26, 16, v24
	v_and_b32_e32 v27, 0xffff0000, v24
	v_lshlrev_b32_e32 v24, 16, v25
	v_and_b32_e32 v25, 0xffff0000, v25
	v_pk_fma_f32 v[188:189], v[188:189], v[22:23], v[24:25]
	v_pk_fma_f32 v[190:191], v[190:191], v[20:21], v[26:27]
	v_cvt_pk_bf16_f32 v21, v188, v189
	v_cvt_pk_bf16_f32 v20, v190, v191
	ds_write_b64 v213, v[20:21] offset:10240
	v_lshl_add_u64 v[20:21], s[28:29], 0, v[158:159]
	global_load_dwordx4 v[24:27], v[20:21], off
	v_lshl_add_u64 v[20:21], v[200:201], 2, s[28:29]
	ds_read_b32 v148, v219 offset:9216
	global_load_dwordx4 v[20:23], v[20:21], off
	s_nop 0
	global_load_dwordx4 v[36:39], v[204:205], off offset:64
	s_nop 0
	global_load_dwordx4 v[28:31], v[28:29], off
	s_nop 0
	global_load_dwordx4 v[32:35], v[204:205], off offset:512
	s_nop 0
	global_load_dwordx4 v[40:43], v[40:41], off
	s_nop 0
	global_load_dwordx4 v[44:47], v[204:205], off offset:576
	v_mul_f32_e32 v155, v145, v145
	v_fmac_f32_e32 v155, v144, v144
	v_add_f32_e32 v154, v154, v155
	v_mul_f32_e32 v155, v143, v143
	v_mul_f32_e32 v161, v141, v141
	v_fmac_f32_e32 v155, v142, v142
	v_fmac_f32_e32 v161, v140, v140
	v_add_f32_e32 v155, v155, v161
	v_add_f32_e32 v154, v154, v155
	v_mul_f32_e32 v155, v139, v139
	v_mul_f32_e32 v161, v137, v137
	v_fmac_f32_e32 v155, v138, v138
	v_fmac_f32_e32 v161, v136, v136
	v_add_f32_e32 v155, v155, v161
	v_add_f32_e32 v154, v154, v155
	v_mul_f32_e32 v155, v127, v127
	v_mul_f32_e32 v161, v125, v125
	v_fmac_f32_e32 v155, v126, v126
	v_fmac_f32_e32 v161, v124, v124
	v_add_f32_e32 v155, v155, v161
	v_add_f32_e32 v154, v154, v155
	v_mov_b32_e32 v155, v154
	v_mov_b32_e32 v204, v154
	s_nop 1
	v_permlane16_swap_b32_e32 v155, v204
	s_waitcnt lgkmcnt(0)
	v_add_f32_e32 v161, v155, v204
	v_mov_b32_e32 v204, v161
	v_mov_b32_e32 v155, v161
	s_nop 1
	v_permlane32_swap_b32_e32 v204, v155
	s_and_saveexec_b64 s[28:29], s[44:45]
	s_cbranch_execz .LBB0_1146
	s_lshl_b32 s30, s33, 10
	s_add_i32 s30, s59, s30
	s_waitcnt lgkmcnt(0)
	v_add_f32_e32 v154, v204, v155
	v_lshl_add_u32 v155, v221, 4, s30
	ds_write_b32 v155, v154
.LBB0_1146:
	s_or_b64 exec, exec, s[28:29]
	v_mul_f32_e32 v154, v135, v135
	v_mul_f32_e32 v155, v133, v133
	v_fmac_f32_e32 v154, v134, v134
	v_fmac_f32_e32 v155, v132, v132
	v_add_f32_e32 v154, v154, v155
	v_mul_f32_e32 v155, v131, v131
	v_mul_f32_e32 v161, v129, v129
	v_fmac_f32_e32 v155, v130, v130
	v_fmac_f32_e32 v161, v128, v128
	v_add_f32_e32 v155, v155, v161
	v_add_f32_e32 v154, v154, v155
	v_mul_f32_e32 v155, v119, v119
	v_mul_f32_e32 v161, v117, v117
	v_fmac_f32_e32 v155, v118, v118
	v_fmac_f32_e32 v161, v116, v116
	v_add_f32_e32 v155, v155, v161
	v_add_f32_e32 v154, v154, v155
	v_mul_f32_e32 v155, v111, v111
	v_mul_f32_e32 v161, v109, v109
	v_fmac_f32_e32 v155, v110, v110
	v_fmac_f32_e32 v161, v108, v108
	v_add_f32_e32 v155, v155, v161
	v_add_f32_e32 v154, v154, v155
	v_mov_b32_e32 v155, v154
	v_mov_b32_e32 v204, v154
	s_nop 1
	v_permlane16_swap_b32_e32 v155, v204
	s_waitcnt lgkmcnt(0)
	v_add_f32_e32 v161, v155, v204
	v_mov_b32_e32 v204, v161
	v_mov_b32_e32 v155, v161
	s_nop 1
	v_permlane32_swap_b32_e32 v204, v155
	s_and_saveexec_b64 s[28:29], s[44:45]
	s_cbranch_execz .LBB0_1148
	s_lshl_b32 s30, s33, 10
	s_add_i32 s30, s59, s30
	s_waitcnt lgkmcnt(0)
	v_add_f32_e32 v154, v204, v155
	v_lshl_add_u32 v155, v221, 4, s30
	ds_write_b32 v155, v154 offset:256
.LBB0_1148:
	s_or_b64 exec, exec, s[28:29]
	v_mul_f32_e32 v154, v123, v123
	v_mul_f32_e32 v155, v121, v121
	v_fmac_f32_e32 v154, v122, v122
	v_fmac_f32_e32 v155, v120, v120
	v_add_f32_e32 v154, v154, v155
	v_mul_f32_e32 v155, v115, v115
	v_mul_f32_e32 v161, v113, v113
	v_fmac_f32_e32 v155, v114, v114
	v_fmac_f32_e32 v161, v112, v112
	v_add_f32_e32 v155, v155, v161
	v_add_f32_e32 v154, v154, v155
	v_mul_f32_e32 v155, v103, v103
	v_mul_f32_e32 v161, v101, v101
	v_fmac_f32_e32 v155, v102, v102
	v_fmac_f32_e32 v161, v100, v100
	v_add_f32_e32 v155, v155, v161
	v_add_f32_e32 v154, v154, v155
	v_mul_f32_e32 v155, v95, v95
	v_mul_f32_e32 v161, v93, v93
	v_fmac_f32_e32 v155, v94, v94
	v_fmac_f32_e32 v161, v92, v92
	v_add_f32_e32 v155, v155, v161
	v_add_f32_e32 v154, v154, v155
	v_mov_b32_e32 v155, v154
	v_mov_b32_e32 v204, v154
	s_nop 1
	v_permlane16_swap_b32_e32 v155, v204
	s_waitcnt lgkmcnt(0)
	v_add_f32_e32 v161, v155, v204
	v_mov_b32_e32 v204, v161
	v_mov_b32_e32 v155, v161
	s_nop 1
	v_permlane32_swap_b32_e32 v204, v155
	s_and_saveexec_b64 s[28:29], s[44:45]
	s_cbranch_execz .LBB0_1150
	s_lshl_b32 s30, s33, 10
	s_add_i32 s30, s59, s30
	s_waitcnt lgkmcnt(0)
	v_add_f32_e32 v154, v204, v155
	v_lshl_add_u32 v155, v221, 4, s30
	ds_write_b32 v155, v154 offset:512
.LBB0_1150:
	s_or_b64 exec, exec, s[28:29]
	v_mul_f32_e32 v154, v107, v107
	v_mul_f32_e32 v155, v105, v105
	v_fmac_f32_e32 v154, v106, v106
	v_fmac_f32_e32 v155, v104, v104
	v_add_f32_e32 v154, v154, v155
	v_mul_f32_e32 v155, v99, v99
	v_mul_f32_e32 v161, v97, v97
	v_fmac_f32_e32 v155, v98, v98
	v_fmac_f32_e32 v161, v96, v96
	v_add_f32_e32 v155, v155, v161
	v_add_f32_e32 v154, v154, v155
	v_mul_f32_e32 v155, v91, v91
	v_mul_f32_e32 v161, v89, v89
	v_fmac_f32_e32 v155, v90, v90
	v_fmac_f32_e32 v161, v88, v88
	v_add_f32_e32 v155, v155, v161
	v_add_f32_e32 v154, v154, v155
	v_mul_f32_e32 v155, v87, v87
	v_mul_f32_e32 v161, v85, v85
	v_fmac_f32_e32 v155, v86, v86
	v_fmac_f32_e32 v161, v84, v84
	v_add_f32_e32 v155, v155, v161
	v_add_f32_e32 v154, v154, v155
	v_mov_b32_e32 v155, v154
	v_mov_b32_e32 v204, v154
	s_nop 1
	v_permlane16_swap_b32_e32 v155, v204
	s_waitcnt lgkmcnt(0)
	v_add_f32_e32 v161, v155, v204
	v_mov_b32_e32 v204, v161
	v_mov_b32_e32 v155, v161
	s_nop 1
	v_permlane32_swap_b32_e32 v204, v155
	s_and_saveexec_b64 s[28:29], s[44:45]
	s_cbranch_execz .LBB0_1152
	s_lshl_b32 s30, s33, 10
	s_add_i32 s30, s59, s30
	s_waitcnt lgkmcnt(0)
	v_add_f32_e32 v154, v204, v155
	v_lshl_add_u32 v155, v221, 4, s30
	ds_write_b32 v155, v154 offset:768
.LBB0_1152:
	s_or_b64 exec, exec, s[28:29]
	v_mul_f32_e32 v154, v83, v83
	v_mul_f32_e32 v155, v81, v81
	v_fmac_f32_e32 v154, v82, v82
	v_fmac_f32_e32 v155, v80, v80
	v_add_f32_e32 v154, v154, v155
	v_mul_f32_e32 v155, v79, v79
	v_mul_f32_e32 v161, v77, v77
	v_fmac_f32_e32 v155, v78, v78
	v_fmac_f32_e32 v161, v76, v76
	v_add_f32_e32 v155, v155, v161
	v_add_f32_e32 v154, v154, v155
	v_mul_f32_e32 v155, v71, v71
	v_mul_f32_e32 v161, v69, v69
	v_fmac_f32_e32 v155, v70, v70
	v_fmac_f32_e32 v161, v68, v68
	v_add_f32_e32 v155, v155, v161
	v_add_f32_e32 v154, v154, v155
	v_mul_f32_e32 v155, v63, v63
	v_mul_f32_e32 v161, v61, v61
	v_fmac_f32_e32 v155, v62, v62
	v_fmac_f32_e32 v161, v60, v60
	v_add_f32_e32 v155, v155, v161
	v_add_f32_e32 v154, v154, v155
	v_mov_b32_e32 v155, v154
	v_mov_b32_e32 v204, v154
	s_nop 1
	v_permlane16_swap_b32_e32 v155, v204
	s_waitcnt lgkmcnt(0)
	v_add_f32_e32 v161, v155, v204
	v_mov_b32_e32 v204, v161
	v_mov_b32_e32 v155, v161
	s_nop 1
	v_permlane32_swap_b32_e32 v204, v155
	s_and_saveexec_b64 s[28:29], s[44:45]
	s_cbranch_execz .LBB0_1154
	s_lshl_b32 s30, s33, 10
	s_add_i32 s30, s59, s30
	s_waitcnt lgkmcnt(0)
	v_add_f32_e32 v154, v204, v155
	v_lshl_add_u32 v155, v221, 4, s30
	ds_write_b32 v155, v154 offset:2048
.LBB0_1154:
	s_or_b64 exec, exec, s[28:29]
	v_mul_f32_e32 v154, v75, v75
	v_mul_f32_e32 v155, v73, v73
	v_fmac_f32_e32 v154, v74, v74
	v_fmac_f32_e32 v155, v72, v72
	v_add_f32_e32 v154, v154, v155
	v_mul_f32_e32 v155, v67, v67
	v_mul_f32_e32 v161, v65, v65
	v_fmac_f32_e32 v155, v66, v66
	v_fmac_f32_e32 v161, v64, v64
	v_add_f32_e32 v155, v155, v161
	v_add_f32_e32 v154, v154, v155
	v_mul_f32_e32 v155, v55, v55
	v_mul_f32_e32 v161, v53, v53
	v_fmac_f32_e32 v155, v54, v54
	v_fmac_f32_e32 v161, v52, v52
	v_add_f32_e32 v155, v155, v161
	v_add_f32_e32 v154, v154, v155
	v_mul_f32_e32 v155, v167, v167
	v_mul_f32_e32 v161, v165, v165
	v_fmac_f32_e32 v155, v166, v166
	v_fmac_f32_e32 v161, v164, v164
	v_add_f32_e32 v155, v155, v161
	v_add_f32_e32 v154, v154, v155
	v_mov_b32_e32 v155, v154
	v_mov_b32_e32 v204, v154
	s_nop 1
	v_permlane16_swap_b32_e32 v155, v204
	s_waitcnt lgkmcnt(0)
	v_add_f32_e32 v161, v155, v204
	v_mov_b32_e32 v204, v161
	v_mov_b32_e32 v155, v161
	s_nop 1
	v_permlane32_swap_b32_e32 v204, v155
	s_and_saveexec_b64 s[28:29], s[44:45]
	s_cbranch_execz .LBB0_1156
	s_lshl_b32 s30, s33, 10
	s_add_i32 s30, s59, s30
	s_waitcnt lgkmcnt(0)
	v_add_f32_e32 v154, v204, v155
	v_lshl_add_u32 v155, v221, 4, s30
	ds_write_b32 v155, v154 offset:2304
.LBB0_1156:
	s_or_b64 exec, exec, s[28:29]
	v_mul_f32_e32 v154, v59, v59
	v_mul_f32_e32 v155, v57, v57
	v_fmac_f32_e32 v154, v58, v58
	v_fmac_f32_e32 v155, v56, v56
	v_add_f32_e32 v154, v154, v155
	v_mul_f32_e32 v155, v51, v51
	v_mul_f32_e32 v161, v49, v49
	v_fmac_f32_e32 v155, v50, v50
	v_fmac_f32_e32 v161, v48, v48
	v_add_f32_e32 v155, v155, v161
	v_add_f32_e32 v154, v154, v155
	v_mul_f32_e32 v155, v171, v171
	v_mul_f32_e32 v161, v169, v169
	v_fmac_f32_e32 v155, v170, v170
	v_fmac_f32_e32 v161, v168, v168
	v_add_f32_e32 v155, v155, v161
	v_add_f32_e32 v154, v154, v155
	v_mul_f32_e32 v155, v175, v175
	v_mul_f32_e32 v161, v173, v173
	v_fmac_f32_e32 v155, v174, v174
	v_fmac_f32_e32 v161, v172, v172
	v_add_f32_e32 v155, v155, v161
	v_add_f32_e32 v154, v154, v155
	v_mov_b32_e32 v155, v154
	v_mov_b32_e32 v204, v154
	s_nop 1
	v_permlane16_swap_b32_e32 v155, v204
	s_waitcnt lgkmcnt(0)
	v_add_f32_e32 v161, v155, v204
	v_mov_b32_e32 v204, v161
	v_mov_b32_e32 v155, v161
	s_nop 1
	v_permlane32_swap_b32_e32 v204, v155
	s_and_saveexec_b64 s[28:29], s[44:45]
	s_cbranch_execz .LBB0_1158
	s_lshl_b32 s30, s33, 10
	s_add_i32 s30, s59, s30
	s_waitcnt lgkmcnt(0)
	v_add_f32_e32 v154, v204, v155
	v_lshl_add_u32 v155, v221, 4, s30
	ds_write_b32 v155, v154 offset:2560
.LBB0_1158:
	s_or_b64 exec, exec, s[28:29]
	v_mul_f32_e32 v154, v179, v179
	v_mul_f32_e32 v155, v177, v177
	v_fmac_f32_e32 v154, v178, v178
	v_fmac_f32_e32 v155, v176, v176
	v_add_f32_e32 v154, v154, v155
	v_mul_f32_e32 v155, v183, v183
	v_mul_f32_e32 v161, v181, v181
	v_fmac_f32_e32 v155, v182, v182
	v_fmac_f32_e32 v161, v180, v180
	v_add_f32_e32 v155, v155, v161
	v_add_f32_e32 v154, v154, v155
	v_mul_f32_e32 v155, v187, v187
	v_mul_f32_e32 v161, v185, v185
	v_fmac_f32_e32 v155, v186, v186
	v_fmac_f32_e32 v161, v184, v184
	v_add_f32_e32 v155, v155, v161
	v_add_f32_e32 v154, v154, v155
	v_mul_f32_e32 v155, v191, v191
	v_mul_f32_e32 v161, v189, v189
	v_fmac_f32_e32 v155, v190, v190
	v_fmac_f32_e32 v161, v188, v188
	v_add_f32_e32 v155, v155, v161
	v_add_f32_e32 v154, v154, v155
	v_mov_b32_e32 v155, v154
	v_mov_b32_e32 v204, v154
	s_nop 1
	v_permlane16_swap_b32_e32 v155, v204
	s_waitcnt lgkmcnt(0)
	v_add_f32_e32 v161, v155, v204
	v_mov_b32_e32 v204, v161
	v_mov_b32_e32 v155, v161
	s_nop 1
	v_permlane32_swap_b32_e32 v204, v155
	s_and_saveexec_b64 s[28:29], s[44:45]
	s_cbranch_execz .LBB0_1160
	s_lshl_b32 s30, s33, 10
	s_add_i32 s30, s59, s30
	s_waitcnt lgkmcnt(0)
	v_add_f32_e32 v154, v204, v155
	v_lshl_add_u32 v155, v221, 4, s30
	ds_write_b32 v155, v154 offset:2816
.LBB0_1160:
	s_or_b64 exec, exec, s[28:29]
	s_waitcnt vmcnt(6)
	v_pk_mul_f32 v[18:19], v[18:19], v[26:27]
	v_pk_mul_f32 v[16:17], v[16:17], v[24:25]
	v_lshlrev_b32_e32 v24, 16, v202
	v_and_b32_e32 v25, 0xffff0000, v202
	v_lshlrev_b32_e32 v26, 16, v203
	v_and_b32_e32 v27, 0xffff0000, v203
	v_pk_mul_f32 v[14:15], v[14:15], v[148:149] op_sel_hi:[1,0]
	v_pk_mul_f32 v[12:13], v[12:13], v[148:149] op_sel_hi:[1,0]
	v_pk_fma_f32 v[202:203], v[18:19], v[14:15], v[26:27]
	s_waitcnt lgkmcnt(0)
	v_pk_fma_f32 v[204:205], v[16:17], v[12:13], v[24:25]
	s_waitcnt vmcnt(4)
	v_pk_mul_f32 v[14:15], v[20:21], v[36:37]
	v_lshlrev_b32_e32 v16, 16, v198
	v_and_b32_e32 v17, 0xffff0000, v198
	v_pk_mul_f32 v[8:9], v[8:9], v[148:149] op_sel_hi:[1,0]
	v_pk_mul_f32 v[12:13], v[22:23], v[38:39]
	v_pk_fma_f32 v[38:39], v[8:9], v[14:15], v[16:17]
	s_waitcnt vmcnt(2)
	v_pk_mul_f32 v[8:9], v[30:31], v[34:35]
	v_lshlrev_b32_e32 v14, 16, v197
	v_and_b32_e32 v15, 0xffff0000, v197
	v_pk_mul_f32 v[6:7], v[6:7], v[148:149] op_sel_hi:[1,0]
	v_lshlrev_b32_e32 v18, 16, v199
	v_and_b32_e32 v19, 0xffff0000, v199
	v_pk_mul_f32 v[10:11], v[10:11], v[148:149] op_sel_hi:[1,0]
	v_pk_fma_f32 v[24:25], v[6:7], v[8:9], v[14:15]
	s_waitcnt vmcnt(0)
	v_pk_mul_f32 v[6:7], v[40:41], v[44:45]
	v_lshlrev_b32_e32 v8, 16, v194
	v_and_b32_e32 v9, 0xffff0000, v194
	v_pk_mul_f32 v[0:1], v[0:1], v[148:149] op_sel_hi:[1,0]
	v_pk_fma_f32 v[36:37], v[10:11], v[12:13], v[18:19]
	v_pk_mul_f32 v[10:11], v[28:29], v[32:33]
	v_lshlrev_b32_e32 v12, 16, v196
	v_and_b32_e32 v13, 0xffff0000, v196
	v_pk_mul_f32 v[4:5], v[4:5], v[148:149] op_sel_hi:[1,0]
	v_pk_fma_f32 v[22:23], v[0:1], v[6:7], v[8:9]
	v_mul_f32_e32 v0, v205, v205
	v_mul_f32_e32 v1, v203, v203
	v_pk_fma_f32 v[26:27], v[4:5], v[10:11], v[12:13]
	v_pk_mul_f32 v[4:5], v[42:43], v[46:47]
	v_lshlrev_b32_e32 v10, 16, v195
	v_and_b32_e32 v11, 0xffff0000, v195
	v_pk_mul_f32 v[2:3], v[2:3], v[148:149] op_sel_hi:[1,0]
	v_fmac_f32_e32 v0, v204, v204
	v_fmac_f32_e32 v1, v202, v202
	v_pk_fma_f32 v[20:21], v[2:3], v[4:5], v[10:11]
	v_add_f32_e32 v0, v0, v1
	v_mul_f32_e32 v1, v39, v39
	v_mul_f32_e32 v2, v37, v37
	v_fmac_f32_e32 v1, v38, v38
	v_fmac_f32_e32 v2, v36, v36
	v_add_f32_e32 v1, v1, v2
	v_add_f32_e32 v0, v0, v1
	v_mul_f32_e32 v1, v27, v27
	v_mul_f32_e32 v2, v25, v25
	v_fmac_f32_e32 v1, v26, v26
	v_fmac_f32_e32 v2, v24, v24
	v_add_f32_e32 v1, v1, v2
	v_add_f32_e32 v0, v0, v1
	v_mul_f32_e32 v1, v23, v23
	v_mul_f32_e32 v2, v21, v21
	v_fmac_f32_e32 v1, v22, v22
	v_fmac_f32_e32 v2, v20, v20
	v_add_f32_e32 v1, v1, v2
	v_add_f32_e32 v0, v0, v1
	v_mov_b32_e32 v1, v0
	v_mov_b32_e32 v2, v0
	s_nop 1
	v_permlane16_swap_b32_e32 v1, v2
	s_waitcnt lgkmcnt(0)
	v_add_f32_e32 v0, v1, v2
	v_mov_b32_e32 v1, v0
	v_mov_b32_e32 v3, v0
	s_nop 1
	v_permlane32_swap_b32_e32 v1, v3
	s_and_saveexec_b64 s[28:29], s[44:45]
	s_cbranch_execz .LBB0_1162
	s_addk_i32 s60, 0x100
	v_or_b32_e32 v2, s60, v221
	v_lshl_add_u32 v2, v2, 4, s59
	s_waitcnt lgkmcnt(0)
	v_add_f32_e32 v0, v1, v3
	ds_write_b32 v2, v0
